# PEER sub-key score MFMA chain: LDS fragment reads issued one k-step ahead (4 A buffers, 2 B buffers) instead of read-wait-mfma per step
# speedup vs baseline: 1.0118x; 1.0022x over previous
; DEV f32x16 mfma32(bf16x8 a, bf16x8 b, f32x16 c) { return __builtin_amdgcn_mfma_f32_32x32x16_bf16(a, b, c, 0, 0, 0); }
; DEV void gemm_core(const bf16_t* __restrict__ A, const bf16_t* __restrict__ Bt, int m0, int n0, bf16_t* As, bf16_t* Bs, int tid,
;                    f32x16 (&acc)[2][2]) {
;     ...
;   for (int kt = 0; kt < 16; ++kt) {
;     __syncthreads();
;     {
;       bf16_t* as = As + lrow * 72 + lc8; bf16_t* bs = Bs + lrow * 72 + lc8;
;       *(uint4*)(as) = ra0; *(uint4*)(as + 32 * 72) = ra1; *(uint4*)(as + 64 * 72) = ra2; *(uint4*)(as + 96 * 72) = ra3;
;       *(uint4*)(bs) = rb0; *(uint4*)(bs + 32 * 72) = rb1; *(uint4*)(bs + 64 * 72) = rb2; *(uint4*)(bs + 96 * 72) = rb3;
;     }
;     __syncthreads();
;     {
;       const int k0 = (kt + 1 < 16) ? (kt + 1) * 64 : 15 * 64;
;       GLOAD(k0);
;     }
; #pragma unroll
;     for (int kk = 0; kk < 4; ++kk) {
;       bf16x8 af[2], bfr[2];
; #pragma unroll
;       for (int mi = 0; mi < 2; ++mi) af[mi] = *(const bf16x8*)(As + (wm * 64 + mi * 32 + lr) * 72 + kk * 16 + hk * 8);
; #pragma unroll
;       for (int ni = 0; ni < 2; ++ni) bfr[ni] = *(const bf16x8*)(Bs + (wn * 64 + ni * 32 + lr) * 72 + kk * 16 + hk * 8);
; #pragma unroll
;       for (int mi = 0; mi < 2; ++mi)
; #pragma unroll
;         for (int ni = 0; ni < 2; ++ni) acc[mi][ni] = mfma32(af[mi], bfr[ni], acc[mi][ni]);
;     }
;   }
.LBB0_46:
	s_barrier
	s_waitcnt vmcnt(6)
	ds_write_b128 v98, v[68:71]
	s_waitcnt vmcnt(5)
	ds_write_b128 v98, v[72:75] offset:4608
	s_waitcnt vmcnt(4)
	ds_write_b128 v98, v[76:79] offset:9216
	s_waitcnt vmcnt(3)
	ds_write_b128 v98, v[80:83] offset:13824
	s_waitcnt vmcnt(3)
	ds_write_b128 v98, v[64:67] offset:18432
	s_waitcnt vmcnt(2)
	ds_write_b128 v98, v[84:87] offset:23040
	s_waitcnt vmcnt(1)
	ds_write_b128 v98, v[88:91] offset:27648
	s_waitcnt vmcnt(0)
	ds_write_b128 v98, v[92:95] offset:32256
	s_waitcnt lgkmcnt(0)
	s_barrier
	ds_read_b128 v[64:67], v189
	ds_read_b128 v[68:71], v190 offset:18432
	ds_read_b128 v[72:75], v189 offset:32
	ds_read_b128 v[76:79], v190 offset:18464
	ds_read_b128 v[80:83], v190 offset:23040
	ds_read_b128 v[84:87], v190 offset:23072
	s_waitcnt lgkmcnt(4)
	v_mfma_f32_32x32x16_bf16 v[48:63], v[64:67], v[68:71], v[48:63]
	s_waitcnt lgkmcnt(1)
	v_mfma_f32_32x32x16_bf16 v[32:47], v[64:67], v[80:83], v[32:47]
	ds_read_b128 v[64:67], v189 offset:4608
	ds_read_b128 v[88:91], v189 offset:4640
	s_waitcnt lgkmcnt(1)
	v_mfma_f32_32x32x16_bf16 v[16:31], v[64:67], v[68:71], v[16:31]
	v_mfma_f32_32x32x16_bf16 v[48:63], v[72:75], v[76:79], v[48:63]
	v_mfma_f32_32x32x16_bf16 v[32:47], v[72:75], v[84:87], v[32:47]
	v_mfma_f32_32x32x16_bf16 v[0:15], v[64:67], v[80:83], v[0:15]
	ds_read_b128 v[64:67], v189 offset:64
	ds_read_b128 v[68:71], v190 offset:18496
	ds_read_b128 v[72:75], v189 offset:96
	ds_read_b128 v[92:95], v190 offset:18528
	v_lshl_add_u64 v[80:81], v[148:149], 0, s[38:39]
	v_lshl_add_u64 v[82:83], v[150:151], 0, s[38:39]
	s_add_u32 s38, s38, 0x80
	s_addc_u32 s39, s39, 0
	s_cmpk_lg_i32 s38, 0x780
	s_waitcnt lgkmcnt(4)
	v_mfma_f32_32x32x16_bf16 v[16:31], v[88:91], v[76:79], v[16:31]
	ds_read_b128 v[76:79], v190 offset:23104
	ds_read_b128 v[192:195], v190 offset:23136
	ds_read_b128 v[196:199], v189 offset:4704
	s_waitcnt lgkmcnt(5)
	v_mfma_f32_32x32x16_bf16 v[48:63], v[64:67], v[68:71], v[48:63]
	s_waitcnt lgkmcnt(2)
	v_mfma_f32_32x32x16_bf16 v[32:47], v[64:67], v[76:79], v[32:47]
	ds_read_b128 v[64:67], v189 offset:4672
	v_mfma_f32_32x32x16_bf16 v[0:15], v[88:91], v[84:87], v[0:15]
	v_add_co_u32_e32 v84, vcc, s42, v80
	s_nop 1
	v_addc_co_u32_e32 v85, vcc, 0, v81, vcc
	v_add_co_u32_e32 v86, vcc, s43, v80
	s_waitcnt lgkmcnt(0)
	v_mfma_f32_32x32x16_bf16 v[16:31], v[64:67], v[68:71], v[16:31]
	v_addc_co_u32_e32 v87, vcc, 0, v81, vcc
	v_add_co_u32_e32 v88, vcc, s44, v80
	s_nop 1
	v_addc_co_u32_e32 v89, vcc, 0, v81, vcc
	v_add_co_u32_e32 v90, vcc, s42, v82
	v_mfma_f32_32x32x16_bf16 v[0:15], v[64:67], v[76:79], v[0:15]
	s_nop 0
	v_addc_co_u32_e32 v91, vcc, 0, v83, vcc
	v_add_co_u32_e32 v200, vcc, s43, v82
	global_load_dwordx4 v[64:67], v[82:83], off offset:128
	s_nop 0
	v_addc_co_u32_e32 v201, vcc, 0, v83, vcc
	v_add_co_u32_e32 v228, vcc, s44, v82
	v_mfma_f32_32x32x16_bf16 v[48:63], v[72:75], v[92:95], v[48:63]
	s_nop 0
	v_addc_co_u32_e32 v229, vcc, 0, v83, vcc
	v_mfma_f32_32x32x16_bf16 v[32:47], v[72:75], v[192:195], v[32:47]
	global_load_dwordx4 v[68:71], v[80:81], off offset:128
	global_load_dwordx4 v[72:75], v[84:85], off offset:128
	global_load_dwordx4 v[76:79], v[86:87], off offset:128
	s_nop 0
	global_load_dwordx4 v[80:83], v[88:89], off offset:128
	global_load_dwordx4 v[84:87], v[90:91], off offset:128
	s_nop 0
	global_load_dwordx4 v[88:91], v[200:201], off offset:128
	v_mfma_f32_32x32x16_bf16 v[16:31], v[196:199], v[92:95], v[16:31]
	global_load_dwordx4 v[92:95], v[228:229], off offset:128
	v_mfma_f32_32x32x16_bf16 v[0:15], v[196:199], v[192:195], v[0:15]
	s_cbranch_scc1 .LBB0_46
	s_barrier
	s_waitcnt vmcnt(6)
	ds_write_b128 v98, v[68:71]
	s_waitcnt vmcnt(5)
	ds_write_b128 v98, v[72:75] offset:4608
	s_waitcnt vmcnt(4)
	ds_write_b128 v98, v[76:79] offset:9216
	s_waitcnt vmcnt(3)
	ds_write_b128 v98, v[80:83] offset:13824
	ds_write_b128 v98, v[64:67] offset:18432
	s_waitcnt vmcnt(2)
	ds_write_b128 v98, v[84:87] offset:23040
	s_waitcnt vmcnt(1)
	ds_write_b128 v98, v[88:91] offset:27648
	s_waitcnt vmcnt(0)
	ds_write_b128 v98, v[92:95] offset:32256
	s_waitcnt lgkmcnt(0)
	s_barrier
	ds_read_b128 v[64:67], v189 offset:4608
	ds_read_b128 v[68:71], v190 offset:23040
	ds_read_b128 v[72:75], v189
	ds_read_b128 v[76:79], v189 offset:32
	ds_read_b128 v[80:83], v190 offset:18432
	ds_read_b128 v[84:87], v190 offset:18464
	s_waitcnt lgkmcnt(1)
	v_mfma_f32_32x32x16_bf16 v[48:63], v[72:75], v[80:83], v[48:63]
	v_readlane_b32 s38, v249, 58
	s_or_b32 s38, s41, s38
	s_ashr_i32 s39, s38, 31
	s_lshl_b64 s[38:39], s[38:39], 8
	s_movk_i32 s41, 0x80
	v_mfma_f32_32x32x16_bf16 v[32:47], v[72:75], v[68:71], v[32:47]
	v_mfma_f32_32x32x16_bf16 v[16:31], v[64:67], v[80:83], v[16:31]
	v_mfma_f32_32x32x16_bf16 v[0:15], v[64:67], v[68:71], v[0:15]
	ds_read_b128 v[64:67], v189 offset:4640
	ds_read_b128 v[68:71], v190 offset:23072
	s_waitcnt lgkmcnt(2)
	v_mfma_f32_32x32x16_bf16 v[48:63], v[76:79], v[84:87], v[48:63]
	s_waitcnt lgkmcnt(0)
	v_mfma_f32_32x32x16_bf16 v[32:47], v[76:79], v[68:71], v[32:47]
	v_mfma_f32_32x32x16_bf16 v[16:31], v[64:67], v[84:87], v[16:31]
	v_mfma_f32_32x32x16_bf16 v[0:15], v[64:67], v[68:71], v[0:15]
	ds_read_b128 v[64:67], v189 offset:64
	ds_read_b128 v[68:71], v189 offset:4672
	ds_read_b128 v[72:75], v190 offset:18496
	ds_read_b128 v[76:79], v190 offset:23104
	s_waitcnt lgkmcnt(1)
	v_mfma_f32_32x32x16_bf16 v[48:63], v[64:67], v[72:75], v[48:63]
	s_waitcnt lgkmcnt(0)
	v_mfma_f32_32x32x16_bf16 v[32:47], v[64:67], v[76:79], v[32:47]
	v_mfma_f32_32x32x16_bf16 v[16:31], v[68:71], v[72:75], v[16:31]
	v_mfma_f32_32x32x16_bf16 v[0:15], v[68:71], v[76:79], v[0:15]
	ds_read_b128 v[64:67], v189 offset:96
	ds_read_b128 v[68:71], v189 offset:4704
	ds_read_b128 v[72:75], v190 offset:18528
	ds_read_b128 v[76:79], v190 offset:23136
	s_waitcnt lgkmcnt(1)
; DEV unsigned short f2bf(float f) { return (unsigned short)(pack2(f, 0.f) & 0xFFFFu); }
; __device__ void peer_q_topk_item(const Params& P, int l, int item, char* smem) {
;     ...
; #pragma unroll
;       for (int mi = 0; mi < 2; ++mi)
; #pragma unroll
;         for (int ni = 0; ni < 2; ++ni) {
;           const int col = wn * 64 + ni * 32 + lr;
;           const int rbase = wm * 64 + mi * 32 + 4 * hk;
; #pragma unroll
;           for (int i = 0; i < 16; ++i) Qs[(rbase + (i & 3) + 8 * (i >> 2)) * 136 + col] = f2bf(acc[mi][ni][i]);
;         }
;     }
;     __syncthreads();
;     {
;       const bf16_t* skg = P.SK + (size_t)((l * 2 + c) * 128) * 128;
; #pragma unroll
;       for (int k = 0; k < 8; ++k) {
;         const int ch = tid + 256 * k;
;         const int row = ch >> 4, c8 = (ch & 15) * 8;
;         *(uint4*)(As + row * 136 + c8) = *(const uint4*)(skg + row * 128 + c8);
;       }
	v_mfma_f32_32x32x16_bf16 v[48:63], v[64:67], v[72:75], v[48:63]
	s_waitcnt lgkmcnt(0)
	v_mfma_f32_32x32x16_bf16 v[32:47], v[64:67], v[76:79], v[32:47]
	s_nop 9
	v_cvt_pk_bf16_f32 v48, v48, s0
	ds_write_b16 v102, v48 offset:36864
	v_cvt_pk_bf16_f32 v48, v49, s0
	ds_write_b16 v183, v48 offset:36864
	v_cvt_pk_bf16_f32 v48, v50, s0
	ds_write_b16 v184, v48 offset:36864
	v_cvt_pk_bf16_f32 v48, v51, s0
	ds_write_b16 v185, v48 offset:36864
	v_cvt_pk_bf16_f32 v48, v52, s0
	ds_write_b16 v186, v48 offset:36864
	v_cvt_pk_bf16_f32 v48, v53, s0
	ds_write_b16 v102, v48 offset:39312
	v_cvt_pk_bf16_f32 v48, v54, s0
	ds_write_b16 v102, v48 offset:39584
	v_cvt_pk_bf16_f32 v48, v55, s0
	ds_write_b16 v102, v48 offset:39856
	v_cvt_pk_bf16_f32 v48, v56, s0
	ds_write_b16 v187, v48 offset:36864
	v_cvt_pk_bf16_f32 v48, v57, s0
	ds_write_b16 v102, v48 offset:41488
	v_cvt_pk_bf16_f32 v48, v58, s0
	ds_write_b16 v102, v48 offset:41760
	v_cvt_pk_bf16_f32 v48, v59, s0
	ds_write_b16 v102, v48 offset:42032
	v_cvt_pk_bf16_f32 v48, v60, s0
	ds_write_b16 v188, v48 offset:36864
	v_cvt_pk_bf16_f32 v48, v61, s0
	ds_write_b16 v102, v48 offset:43664
	v_cvt_pk_bf16_f32 v48, v62, s0
	v_cvt_pk_bf16_f32 v32, v32, s0
	ds_write_b16 v102, v48 offset:43936
	v_cvt_pk_bf16_f32 v48, v63, s0
	ds_write_b16 v102, v32 offset:36928
	v_cvt_pk_bf16_f32 v32, v33, s0
	ds_write_b16 v102, v48 offset:44208
	ds_write_b16 v183, v32 offset:36928
	v_cvt_pk_bf16_f32 v32, v34, s0
	ds_write_b16 v184, v32 offset:36928
	v_cvt_pk_bf16_f32 v32, v35, s0
	v_mfma_f32_32x32x16_bf16 v[0:15], v[68:71], v[76:79], v[0:15]
	ds_write_b16 v185, v32 offset:36928
	v_cvt_pk_bf16_f32 v32, v36, s0
	ds_write_b16 v186, v32 offset:36928
	v_cvt_pk_bf16_f32 v32, v37, s0
	ds_write_b16 v102, v32 offset:39376
	v_cvt_pk_bf16_f32 v32, v38, s0
	ds_write_b16 v102, v32 offset:39648
	v_mfma_f32_32x32x16_bf16 v[16:31], v[68:71], v[72:75], v[16:31]
	v_cvt_pk_bf16_f32 v32, v39, s0
	ds_write_b16 v102, v32 offset:39920
	v_cvt_pk_bf16_f32 v32, v40, s0
	ds_write_b16 v187, v32 offset:36928
	v_cvt_pk_bf16_f32 v32, v41, s0
	ds_write_b16 v102, v32 offset:41552
	v_cvt_pk_bf16_f32 v32, v42, s0
	ds_write_b16 v102, v32 offset:41824
	v_cvt_pk_bf16_f32 v32, v43, s0
	ds_write_b16 v102, v32 offset:42096
	v_cvt_pk_bf16_f32 v32, v44, s0
	v_cvt_pk_bf16_f32 v0, v0, s0
	ds_write_b16 v188, v32 offset:36928
	v_cvt_pk_bf16_f32 v16, v16, s0
	ds_write_b16 v102, v0 offset:45632
	v_cvt_pk_bf16_f32 v0, v1, s0
	ds_write_b16 v102, v16 offset:45568
	v_cvt_pk_bf16_f32 v16, v17, s0
	ds_write_b16 v102, v0 offset:45904
	v_cvt_pk_bf16_f32 v0, v2, s0
	ds_write_b16 v102, v16 offset:45840
	v_cvt_pk_bf16_f32 v16, v18, s0
	ds_write_b16 v102, v0 offset:46176
	v_cvt_pk_bf16_f32 v0, v3, s0
	ds_write_b16 v102, v16 offset:46112
	v_cvt_pk_bf16_f32 v16, v19, s0
	ds_write_b16 v102, v0 offset:46448
	v_cvt_pk_bf16_f32 v0, v4, s0
	ds_write_b16 v102, v16 offset:46384
	v_cvt_pk_bf16_f32 v16, v20, s0
	ds_write_b16 v102, v0 offset:47808
	v_cvt_pk_bf16_f32 v0, v5, s0
	ds_write_b16 v102, v16 offset:47744
	v_cvt_pk_bf16_f32 v16, v21, s0
	ds_write_b16 v102, v0 offset:48080
	v_cvt_pk_bf16_f32 v0, v6, s0
	ds_write_b16 v102, v16 offset:48016
	v_cvt_pk_bf16_f32 v16, v22, s0
	ds_write_b16 v102, v0 offset:48352
	v_cvt_pk_bf16_f32 v0, v7, s0
	ds_write_b16 v102, v16 offset:48288
	v_cvt_pk_bf16_f32 v16, v23, s0
	ds_write_b16 v102, v0 offset:48624
	v_cvt_pk_bf16_f32 v0, v8, s0
	ds_write_b16 v102, v16 offset:48560
	v_cvt_pk_bf16_f32 v16, v24, s0
	ds_write_b16 v102, v0 offset:49984
	v_cvt_pk_bf16_f32 v0, v9, s0
	ds_write_b16 v102, v16 offset:49920
	v_cvt_pk_bf16_f32 v16, v25, s0
	ds_write_b16 v102, v0 offset:50256
	v_cvt_pk_bf16_f32 v0, v10, s0
	ds_write_b16 v102, v16 offset:50192
	v_cvt_pk_bf16_f32 v16, v26, s0
	ds_write_b16 v102, v0 offset:50528
	v_cvt_pk_bf16_f32 v0, v11, s0
	ds_write_b16 v102, v16 offset:50464
	v_cvt_pk_bf16_f32 v16, v27, s0
	ds_write_b16 v102, v0 offset:50800
	v_cvt_pk_bf16_f32 v0, v12, s0
	ds_write_b16 v102, v16 offset:50736
	v_cvt_pk_bf16_f32 v16, v28, s0
	ds_write_b16 v102, v0 offset:52160
	v_cvt_pk_bf16_f32 v0, v13, s0
	v_cvt_pk_bf16_f32 v32, v45, s0
	ds_write_b16 v102, v16 offset:52096
	v_cvt_pk_bf16_f32 v16, v29, s0
	ds_write_b16 v102, v0 offset:52432
	v_cvt_pk_bf16_f32 v0, v14, s0
	ds_write_b16 v102, v32 offset:43728
	v_cvt_pk_bf16_f32 v32, v46, s0
	ds_write_b16 v102, v16 offset:52368
	v_cvt_pk_bf16_f32 v16, v30, s0
	ds_write_b16 v102, v0 offset:52704
	v_cvt_pk_bf16_f32 v0, v15, s0
	v_lshl_add_u64 v[4:5], v[146:147], 0, s[38:39]
	ds_write_b16 v102, v32 offset:44000
	v_cvt_pk_bf16_f32 v32, v47, s0
	ds_write_b16 v102, v16 offset:52640
	v_cvt_pk_bf16_f32 v16, v31, s0
	ds_write_b16 v102, v0 offset:52976
	v_lshl_add_u64 v[0:1], v[104:105], 1, v[4:5]
	ds_write_b16 v102, v32 offset:44272
	ds_write_b16 v102, v16 offset:52912
	global_load_dwordx4 v[64:67], v[0:1], off
	v_lshl_add_u64 v[0:1], v[108:109], 1, v[4:5]
	global_load_dwordx4 v[68:71], v[0:1], off
	v_lshl_add_u64 v[0:1], v[112:113], 1, v[4:5]
	global_load_dwordx4 v[72:75], v[0:1], off
	v_lshl_add_u64 v[0:1], v[116:117], 1, v[4:5]
	global_load_dwordx4 v[76:79], v[0:1], off
	v_lshl_add_u64 v[0:1], v[120:121], 1, v[4:5]
	global_load_dwordx4 v[80:83], v[0:1], off
	v_lshl_add_u64 v[0:1], v[124:125], 1, v[4:5]
	global_load_dwordx4 v[84:87], v[0:1], off
	v_lshl_add_u64 v[0:1], v[128:129], 1, v[4:5]
	global_load_dwordx4 v[88:91], v[0:1], off
	v_lshl_add_u64 v[0:1], v[132:133], 1, v[4:5]
	global_load_dwordx4 v[92:95], v[0:1], off
	s_waitcnt lgkmcnt(0)
	s_barrier
; DEV f32x16 mfma32(bf16x8 a, bf16x8 b, f32x16 c) { return __builtin_amdgcn_mfma_f32_32x32x16_bf16(a, b, c, 0, 0, 0); }
; __device__ void peer_q_topk_item(const Params& P, int l, int item, char* smem) {
;     ...
;     __syncthreads();
;     {
;       const bf16_t* skg = P.SK + (size_t)((l * 2 + c) * 128) * 128;
; #pragma unroll
;       for (int k = 0; k < 8; ++k) {
;         const int ch = tid + 256 * k;
;         const int row = ch >> 4, c8 = (ch & 15) * 8;
;         *(uint4*)(As + row * 136 + c8) = *(const uint4*)(skg + row * 128 + c8);
;       }
;     }
;     __syncthreads();
;     unsigned Lc[16];
;     {
;       f32x16 sa[4];
; #pragma unroll
;       for (int m4 = 0; m4 < 4; ++m4)
; #pragma unroll
;         for (int i = 0; i < 16; ++i) sa[m4][i] = 0.f;
;       const bf16_t* qrow = Qs + (w * 32 + q) * 136 + hk * 8;
;       const bf16_t* sk = As + q * 136 + hk * 8;
; #pragma unroll
;       for (int ks = 0; ks < 8; ++ks) {
;         const bf16x8 bq = *(const bf16x8*)(qrow + ks * 16);
; #pragma unroll
;         for (int m4 = 0; m4 < 4; ++m4) {
;           const bf16x8 a = *(const bf16x8*)(sk + (m4 * 32) * 136 + ks * 16);
;           sa[m4] = mfma32(a, bq, sa[m4]);
;         }
;       }
	s_movk_i32 s39, 0x7f
	s_movk_i32 s38, 0x5f
	s_waitcnt vmcnt(7)
	ds_write_b128 v106, v[64:67]
	s_waitcnt vmcnt(6)
	ds_write_b128 v110, v[68:71]
	s_waitcnt vmcnt(5)
	ds_write_b128 v114, v[72:75]
	s_waitcnt vmcnt(4)
	ds_write_b128 v118, v[76:79]
	s_waitcnt vmcnt(3)
	ds_write_b128 v122, v[80:83]
	s_waitcnt vmcnt(2)
	ds_write_b128 v126, v[84:87]
	s_waitcnt vmcnt(1)
	ds_write_b128 v130, v[88:91]
	s_waitcnt vmcnt(0)
	ds_write_b128 v134, v[92:95]
	s_waitcnt lgkmcnt(0)
	s_barrier
	ds_read_b128 v[0:3], v100 offset:36864
	ds_read_b128 v[64:67], v100 offset:36896
	ds_read_b128 v[4:7], v160
	ds_read_b128 v[68:71], v160 offset:32
	s_waitcnt lgkmcnt(1)
	v_mfma_f32_32x32x16_bf16 v[48:63], v[4:7], v[0:3], 0
	ds_read_b128 v[4:7], v160 offset:8704
	s_waitcnt lgkmcnt(1)
	v_mfma_f32_32x32x16_bf16 v[48:63], v[68:71], v[64:67], v[48:63]
	ds_read_b128 v[68:71], v160 offset:8736
	s_waitcnt lgkmcnt(1)
	v_mfma_f32_32x32x16_bf16 v[32:47], v[4:7], v[0:3], 0
	ds_read_b128 v[4:7], v160 offset:17408
	s_waitcnt lgkmcnt(1)
	v_mfma_f32_32x32x16_bf16 v[32:47], v[68:71], v[64:67], v[32:47]
	ds_read_b128 v[68:71], v160 offset:17440
	s_waitcnt lgkmcnt(1)
	v_mfma_f32_32x32x16_bf16 v[16:31], v[4:7], v[0:3], 0
	ds_read_b128 v[4:7], v160 offset:26112
	s_waitcnt lgkmcnt(1)
	v_mfma_f32_32x32x16_bf16 v[16:31], v[68:71], v[64:67], v[16:31]
	ds_read_b128 v[68:71], v160 offset:26144
	s_waitcnt lgkmcnt(1)
	v_mfma_f32_32x32x16_bf16 v[0:15], v[4:7], v[0:3], 0
	s_waitcnt lgkmcnt(0)
	v_mfma_f32_32x32x16_bf16 v[0:15], v[68:71], v[64:67], v[0:15]
	ds_read_b128 v[64:67], v100 offset:36928
	ds_read_b128 v[68:71], v160 offset:64
	ds_read_b128 v[72:75], v160 offset:8768
	ds_read_b128 v[80:83], v160 offset:17472
	ds_read_b128 v[84:87], v160 offset:26176
	ds_read_b128 v[76:79], v100 offset:36960
	s_waitcnt lgkmcnt(4)
	v_mfma_f32_32x32x16_bf16 v[48:63], v[68:71], v[64:67], v[48:63]
	ds_read_b128 v[68:71], v160 offset:96
	s_waitcnt lgkmcnt(4)
	v_mfma_f32_32x32x16_bf16 v[32:47], v[72:75], v[64:67], v[32:47]
	ds_read_b128 v[72:75], v160 offset:8800
	s_waitcnt lgkmcnt(4)
	v_mfma_f32_32x32x16_bf16 v[16:31], v[80:83], v[64:67], v[16:31]
	ds_read_b128 v[80:83], v160 offset:17504
	s_waitcnt lgkmcnt(4)
	v_mfma_f32_32x32x16_bf16 v[0:15], v[84:87], v[64:67], v[0:15]
	ds_read_b128 v[84:87], v160 offset:26208
	ds_read_b128 v[64:67], v100 offset:36992
	s_waitcnt lgkmcnt(4)
	v_mfma_f32_32x32x16_bf16 v[48:63], v[68:71], v[76:79], v[48:63]
	ds_read_b128 v[68:71], v160 offset:128
	s_waitcnt lgkmcnt(4)
	v_mfma_f32_32x32x16_bf16 v[32:47], v[72:75], v[76:79], v[32:47]
	ds_read_b128 v[72:75], v160 offset:8832
	s_waitcnt lgkmcnt(4)
	v_mfma_f32_32x32x16_bf16 v[16:31], v[80:83], v[76:79], v[16:31]
	ds_read_b128 v[80:83], v160 offset:17536
	s_waitcnt lgkmcnt(4)
	v_mfma_f32_32x32x16_bf16 v[0:15], v[84:87], v[76:79], v[0:15]
	ds_read_b128 v[84:87], v160 offset:26240
	ds_read_b128 v[76:79], v100 offset:37024
	s_waitcnt lgkmcnt(4)
	v_mfma_f32_32x32x16_bf16 v[48:63], v[68:71], v[64:67], v[48:63]
	ds_read_b128 v[68:71], v160 offset:160
	s_waitcnt lgkmcnt(4)
	v_mfma_f32_32x32x16_bf16 v[32:47], v[72:75], v[64:67], v[32:47]
	ds_read_b128 v[72:75], v160 offset:8864
	s_waitcnt lgkmcnt(4)
	v_mfma_f32_32x32x16_bf16 v[16:31], v[80:83], v[64:67], v[16:31]
	ds_read_b128 v[80:83], v160 offset:17568
	s_waitcnt lgkmcnt(4)
	v_mfma_f32_32x32x16_bf16 v[0:15], v[84:87], v[64:67], v[0:15]
	ds_read_b128 v[84:87], v160 offset:26272
	ds_read_b128 v[64:67], v100 offset:37056
	s_waitcnt lgkmcnt(4)
	v_mfma_f32_32x32x16_bf16 v[48:63], v[68:71], v[76:79], v[48:63]
	ds_read_b128 v[68:71], v160 offset:192
	s_waitcnt lgkmcnt(4)
	v_mfma_f32_32x32x16_bf16 v[32:47], v[72:75], v[76:79], v[32:47]
	ds_read_b128 v[72:75], v160 offset:8896
	s_waitcnt lgkmcnt(4)
	v_mfma_f32_32x32x16_bf16 v[16:31], v[80:83], v[76:79], v[16:31]
	ds_read_b128 v[80:83], v160 offset:17600
	s_waitcnt lgkmcnt(4)
	v_mfma_f32_32x32x16_bf16 v[0:15], v[84:87], v[76:79], v[0:15]
	ds_read_b128 v[84:87], v160 offset:26304
	ds_read_b128 v[76:79], v100 offset:37088
	s_waitcnt lgkmcnt(4)
	v_mfma_f32_32x32x16_bf16 v[48:63], v[68:71], v[64:67], v[48:63]
	ds_read_b128 v[68:71], v160 offset:224
	s_waitcnt lgkmcnt(4)
	v_mfma_f32_32x32x16_bf16 v[32:47], v[72:75], v[64:67], v[32:47]
	ds_read_b128 v[72:75], v160 offset:8928
	s_waitcnt lgkmcnt(4)
	v_mfma_f32_32x32x16_bf16 v[16:31], v[80:83], v[64:67], v[16:31]
	ds_read_b128 v[80:83], v160 offset:17632
	s_waitcnt lgkmcnt(4)
	v_mfma_f32_32x32x16_bf16 v[0:15], v[84:87], v[64:67], v[0:15]
	ds_read_b128 v[84:87], v160 offset:26336
	s_waitcnt lgkmcnt(3)
	v_mfma_f32_32x32x16_bf16 v[48:63], v[68:71], v[76:79], v[48:63]
	s_waitcnt lgkmcnt(2)
	v_mfma_f32_32x32x16_bf16 v[32:47], v[72:75], v[76:79], v[32:47]
	s_waitcnt lgkmcnt(1)
	v_mfma_f32_32x32x16_bf16 v[16:31], v[80:83], v[76:79], v[16:31]
	s_waitcnt lgkmcnt(0)
; DEV f32x16 mfma32(bf16x8 a, bf16x8 b, f32x16 c) { return __builtin_amdgcn_mfma_f32_32x32x16_bf16(a, b, c, 0, 0, 0); }
; DEV unsigned fkey(float v) { const unsigned u = __float_as_uint(v); return (u & 0x80000000u) ? ~u : (u | 0x80000000u); }
; __device__ void peer_q_topk_item(const Params& P, int l, int item, char* smem) {
;     ...
;       for (int ks = 0; ks < 8; ++ks) {
;         const bf16x8 bq = *(const bf16x8*)(qrow + ks * 16);
; #pragma unroll
;         for (int m4 = 0; m4 < 4; ++m4) {
;           const bf16x8 a = *(const bf16x8*)(sk + (m4 * 32) * 136 + ks * 16);
;           sa[m4] = mfma32(a, bq, sa[m4]);
;         }
;       }
;       unsigned G1[16], G2[16], G3[16];
; #pragma unroll
;       for (int i = 0; i < 16; ++i) {
;         const int kb0 = (i & 3) + 8 * (i >> 2) + 4 * hk;
;         Lc[i] = (fkey(sa[0][i]) & ~0x7Fu) | (unsigned)(127 - kb0);
;         G1[i] = (fkey(sa[1][i]) & ~0x7Fu) | (unsigned)(127 - (32 + kb0));
;         G2[i] = (fkey(sa[2][i]) & ~0x7Fu) | (unsigned)(127 - (64 + kb0));
;         G3[i] = (fkey(sa[3][i]) & ~0x7Fu) | (unsigned)(127 - (96 + kb0));
;       }
	v_mfma_f32_32x32x16_bf16 v[0:15], v[84:87], v[76:79], v[0:15]
	s_nop 7
	v_cmp_gt_i32_e32 vcc, 0, v48
	v_not_b32_e32 v64, v48
	v_or_b32_e32 v65, 0x80000000, v48
	v_cndmask_b32_e32 v48, v65, v64, vcc
	v_not_b32_e32 v64, v32
	v_or_b32_e32 v65, 0x80000000, v32
	v_cmp_gt_i32_e32 vcc, 0, v32
	v_and_b32_e32 v48, 0xffffff80, v48
	v_bitop3_b32 v48, v48, s39, v159 bitop3:0x36
	v_cndmask_b32_e32 v32, v65, v64, vcc
	v_not_b32_e32 v64, v16
	v_or_b32_e32 v65, 0x80000000, v16
	v_cmp_gt_i32_e32 vcc, 0, v16
	v_and_b32_e32 v32, 0xffffff80, v32
	v_bitop3_b32 v32, v32, s38, v159 bitop3:0x36
	v_cndmask_b32_e32 v16, v65, v64, vcc
	v_not_b32_e32 v64, v0
	v_or_b32_e32 v65, 0x80000000, v0
	v_cmp_gt_i32_e32 vcc, 0, v0
	v_and_b32_e32 v16, 0xffffff80, v16
	v_bitop3_b32 v16, v16, 63, v159 bitop3:0x36
	v_cndmask_b32_e32 v0, v65, v64, vcc
	v_not_b32_e32 v64, v49
	v_or_b32_e32 v65, 0x80000000, v49
	v_cmp_gt_i32_e32 vcc, 0, v49
	v_and_b32_e32 v0, 0xffffff80, v0
	v_bitop3_b32 v0, v0, 31, v159 bitop3:0x36
	v_cndmask_b32_e32 v49, v65, v64, vcc
	v_not_b32_e32 v64, v33
	v_or_b32_e32 v65, 0x80000000, v33
	v_cmp_gt_i32_e32 vcc, 0, v33
	v_and_b32_e32 v49, 0xffffff80, v49
	v_bitop3_b32 v49, v49, s39, v163 bitop3:0x36
	v_cndmask_b32_e32 v33, v65, v64, vcc
	v_not_b32_e32 v64, v17
	v_or_b32_e32 v65, 0x80000000, v17
	v_cmp_gt_i32_e32 vcc, 0, v17
	v_and_b32_e32 v33, 0xffffff80, v33
	v_bitop3_b32 v33, v33, s38, v163 bitop3:0x36
	v_cndmask_b32_e32 v17, v65, v64, vcc
	v_not_b32_e32 v64, v1
	v_or_b32_e32 v65, 0x80000000, v1
	v_cmp_gt_i32_e32 vcc, 0, v1
	v_and_b32_e32 v17, 0xffffff80, v17
	v_bitop3_b32 v17, v17, 63, v163 bitop3:0x36
	v_cndmask_b32_e32 v1, v65, v64, vcc
	v_not_b32_e32 v64, v50
	v_or_b32_e32 v65, 0x80000000, v50
	v_cmp_gt_i32_e32 vcc, 0, v50
	v_and_b32_e32 v1, 0xffffff80, v1
	v_bitop3_b32 v1, v1, 31, v163 bitop3:0x36
	v_cndmask_b32_e32 v50, v65, v64, vcc
	v_not_b32_e32 v64, v34
	v_or_b32_e32 v65, 0x80000000, v34
	v_cmp_gt_i32_e32 vcc, 0, v34
	v_and_b32_e32 v50, 0xffffff80, v50
	v_bitop3_b32 v50, v50, s39, v164 bitop3:0x36
	v_cndmask_b32_e32 v34, v65, v64, vcc
	v_not_b32_e32 v64, v18
	v_or_b32_e32 v65, 0x80000000, v18
	v_cmp_gt_i32_e32 vcc, 0, v18
	v_and_b32_e32 v34, 0xffffff80, v34
	v_bitop3_b32 v34, v34, s38, v164 bitop3:0x36
	v_cndmask_b32_e32 v18, v65, v64, vcc
	v_not_b32_e32 v64, v2
	v_or_b32_e32 v65, 0x80000000, v2
	v_cmp_gt_i32_e32 vcc, 0, v2
	v_and_b32_e32 v18, 0xffffff80, v18
	v_bitop3_b32 v18, v18, 63, v164 bitop3:0x36
	v_cndmask_b32_e32 v2, v65, v64, vcc
	v_not_b32_e32 v64, v51
	v_or_b32_e32 v65, 0x80000000, v51
	v_cmp_gt_i32_e32 vcc, 0, v51
	v_and_b32_e32 v2, 0xffffff80, v2
	v_bitop3_b32 v2, v2, 31, v164 bitop3:0x36
	v_cndmask_b32_e32 v51, v65, v64, vcc
	v_not_b32_e32 v64, v35
	v_or_b32_e32 v65, 0x80000000, v35
	v_cmp_gt_i32_e32 vcc, 0, v35
	v_and_b32_e32 v51, 0xffffff80, v51
	v_bitop3_b32 v51, v51, s39, v166 bitop3:0x36
	v_cndmask_b32_e32 v35, v65, v64, vcc
	v_not_b32_e32 v64, v19
	v_or_b32_e32 v65, 0x80000000, v19
	v_cmp_gt_i32_e32 vcc, 0, v19
	v_and_b32_e32 v35, 0xffffff80, v35
	v_bitop3_b32 v35, v35, s38, v166 bitop3:0x36
	v_cndmask_b32_e32 v19, v65, v64, vcc
	v_not_b32_e32 v64, v3
	v_or_b32_e32 v65, 0x80000000, v3
	v_cmp_gt_i32_e32 vcc, 0, v3
	v_and_b32_e32 v19, 0xffffff80, v19
	v_bitop3_b32 v19, v19, 63, v166 bitop3:0x36
	v_cndmask_b32_e32 v3, v65, v64, vcc
	v_not_b32_e32 v64, v52
	v_or_b32_e32 v65, 0x80000000, v52
	v_cmp_gt_i32_e32 vcc, 0, v52
	v_and_b32_e32 v3, 0xffffff80, v3
	v_bitop3_b32 v3, v3, 31, v166 bitop3:0x36
	v_cndmask_b32_e32 v52, v65, v64, vcc
	v_not_b32_e32 v64, v36
	v_or_b32_e32 v65, 0x80000000, v36
	v_cmp_gt_i32_e32 vcc, 0, v36
	v_and_b32_e32 v52, 0xffffff80, v52
	v_bitop3_b32 v52, v52, s39, v167 bitop3:0x36
	v_cndmask_b32_e32 v36, v65, v64, vcc
	v_not_b32_e32 v64, v20
	v_or_b32_e32 v65, 0x80000000, v20
	v_cmp_gt_i32_e32 vcc, 0, v20
	v_and_b32_e32 v36, 0xffffff80, v36
	v_bitop3_b32 v36, v36, s38, v167 bitop3:0x36
	v_cndmask_b32_e32 v20, v65, v64, vcc
	v_not_b32_e32 v64, v4
	v_or_b32_e32 v65, 0x80000000, v4
	v_cmp_gt_i32_e32 vcc, 0, v4
	v_and_b32_e32 v20, 0xffffff80, v20
	v_bitop3_b32 v20, v20, 63, v167 bitop3:0x36
	v_cndmask_b32_e32 v4, v65, v64, vcc
	v_not_b32_e32 v64, v53
	v_or_b32_e32 v65, 0x80000000, v53
	v_cmp_gt_i32_e32 vcc, 0, v53
	v_and_b32_e32 v4, 0xffffff80, v4
	v_bitop3_b32 v4, v4, 31, v167 bitop3:0x36
	v_cndmask_b32_e32 v53, v65, v64, vcc
	v_not_b32_e32 v64, v37
	v_or_b32_e32 v65, 0x80000000, v37
	v_cmp_gt_i32_e32 vcc, 0, v37
	v_and_b32_e32 v53, 0xffffff80, v53
	v_bitop3_b32 v53, v53, s39, v171 bitop3:0x36
	v_cndmask_b32_e32 v37, v65, v64, vcc
	v_not_b32_e32 v64, v21
	v_or_b32_e32 v65, 0x80000000, v21
	v_cmp_gt_i32_e32 vcc, 0, v21
	v_and_b32_e32 v37, 0xffffff80, v37
	v_bitop3_b32 v37, v37, s38, v171 bitop3:0x36
	v_cndmask_b32_e32 v21, v65, v64, vcc
	v_not_b32_e32 v64, v5
	v_or_b32_e32 v65, 0x80000000, v5
	v_cmp_gt_i32_e32 vcc, 0, v5
	v_and_b32_e32 v21, 0xffffff80, v21
	v_bitop3_b32 v21, v21, 63, v171 bitop3:0x36
	v_cndmask_b32_e32 v5, v65, v64, vcc
	v_not_b32_e32 v64, v54
	v_or_b32_e32 v65, 0x80000000, v54
	v_cmp_gt_i32_e32 vcc, 0, v54
	v_and_b32_e32 v5, 0xffffff80, v5
	v_bitop3_b32 v5, v5, 31, v171 bitop3:0x36
	v_cndmask_b32_e32 v54, v65, v64, vcc
	v_not_b32_e32 v64, v38
	v_or_b32_e32 v65, 0x80000000, v38
	v_cmp_gt_i32_e32 vcc, 0, v38
	v_and_b32_e32 v54, 0xffffff80, v54
	v_bitop3_b32 v54, v54, s39, v172 bitop3:0x36
	v_cndmask_b32_e32 v38, v65, v64, vcc
	v_not_b32_e32 v64, v22
	v_or_b32_e32 v65, 0x80000000, v22
	v_cmp_gt_i32_e32 vcc, 0, v22
	v_and_b32_e32 v38, 0xffffff80, v38
	v_bitop3_b32 v38, v38, s38, v172 bitop3:0x36
	v_cndmask_b32_e32 v22, v65, v64, vcc
	v_not_b32_e32 v64, v6
	v_or_b32_e32 v65, 0x80000000, v6
; DEV unsigned fkey(float v) { const unsigned u = __float_as_uint(v); return (u & 0x80000000u) ? ~u : (u | 0x80000000u); }
; __device__ void peer_q_topk_item(const Params& P, int l, int item, char* smem) {
;     ...
;       unsigned G1[16], G2[16], G3[16];
; #pragma unroll
;       for (int i = 0; i < 16; ++i) {
;         const int kb0 = (i & 3) + 8 * (i >> 2) + 4 * hk;
;         Lc[i] = (fkey(sa[0][i]) & ~0x7Fu) | (unsigned)(127 - kb0);
;         G1[i] = (fkey(sa[1][i]) & ~0x7Fu) | (unsigned)(127 - (32 + kb0));
;         G2[i] = (fkey(sa[2][i]) & ~0x7Fu) | (unsigned)(127 - (64 + kb0));
;         G3[i] = (fkey(sa[3][i]) & ~0x7Fu) | (unsigned)(127 - (96 + kb0));
;       }
	v_cmp_gt_i32_e32 vcc, 0, v6
	v_and_b32_e32 v22, 0xffffff80, v22
	v_bitop3_b32 v22, v22, 63, v172 bitop3:0x36
	v_cndmask_b32_e32 v6, v65, v64, vcc
	v_not_b32_e32 v64, v55
	v_or_b32_e32 v65, 0x80000000, v55
	v_cmp_gt_i32_e32 vcc, 0, v55
	v_and_b32_e32 v6, 0xffffff80, v6
	v_bitop3_b32 v6, v6, 31, v172 bitop3:0x36
	v_cndmask_b32_e32 v55, v65, v64, vcc
	v_not_b32_e32 v64, v39
	v_or_b32_e32 v65, 0x80000000, v39
	v_cmp_gt_i32_e32 vcc, 0, v39
	v_and_b32_e32 v55, 0xffffff80, v55
	v_bitop3_b32 v55, v55, s39, v173 bitop3:0x36
	v_cndmask_b32_e32 v39, v65, v64, vcc
	v_not_b32_e32 v64, v23
	v_or_b32_e32 v65, 0x80000000, v23
	v_cmp_gt_i32_e32 vcc, 0, v23
	v_and_b32_e32 v39, 0xffffff80, v39
	v_bitop3_b32 v39, v39, s38, v173 bitop3:0x36
	v_cndmask_b32_e32 v23, v65, v64, vcc
	v_not_b32_e32 v64, v7
	v_or_b32_e32 v65, 0x80000000, v7
	v_cmp_gt_i32_e32 vcc, 0, v7
	v_and_b32_e32 v23, 0xffffff80, v23
	v_bitop3_b32 v23, v23, 63, v173 bitop3:0x36
	v_cndmask_b32_e32 v7, v65, v64, vcc
	v_not_b32_e32 v64, v56
	v_or_b32_e32 v65, 0x80000000, v56
	v_cmp_gt_i32_e32 vcc, 0, v56
	v_and_b32_e32 v7, 0xffffff80, v7
	v_bitop3_b32 v7, v7, 31, v173 bitop3:0x36
	v_cndmask_b32_e32 v56, v65, v64, vcc
	v_not_b32_e32 v64, v40
	v_or_b32_e32 v65, 0x80000000, v40
	v_cmp_gt_i32_e32 vcc, 0, v40
	v_and_b32_e32 v56, 0xffffff80, v56
	v_bitop3_b32 v56, v56, s39, v169 bitop3:0x36
	v_cndmask_b32_e32 v40, v65, v64, vcc
	v_not_b32_e32 v64, v24
	v_or_b32_e32 v65, 0x80000000, v24
	v_cmp_gt_i32_e32 vcc, 0, v24
	v_and_b32_e32 v40, 0xffffff80, v40
	v_bitop3_b32 v40, v40, s38, v169 bitop3:0x36
	v_cndmask_b32_e32 v24, v65, v64, vcc
	v_not_b32_e32 v64, v8
	v_or_b32_e32 v65, 0x80000000, v8
	v_cmp_gt_i32_e32 vcc, 0, v8
	v_and_b32_e32 v24, 0xffffff80, v24
	v_bitop3_b32 v24, v24, 63, v169 bitop3:0x36
	v_cndmask_b32_e32 v8, v65, v64, vcc
	v_not_b32_e32 v64, v57
	v_or_b32_e32 v65, 0x80000000, v57
	v_cmp_gt_i32_e32 vcc, 0, v57
	v_and_b32_e32 v8, 0xffffff80, v8
	v_bitop3_b32 v8, v8, 31, v169 bitop3:0x36
	v_cndmask_b32_e32 v57, v65, v64, vcc
	v_not_b32_e32 v64, v41
	v_or_b32_e32 v65, 0x80000000, v41
	v_cmp_gt_i32_e32 vcc, 0, v41
	v_and_b32_e32 v57, 0xffffff80, v57
	v_bitop3_b32 v57, v57, s39, v174 bitop3:0x36
	v_cndmask_b32_e32 v41, v65, v64, vcc
	v_not_b32_e32 v64, v25
	v_or_b32_e32 v65, 0x80000000, v25
	v_cmp_gt_i32_e32 vcc, 0, v25
	v_and_b32_e32 v41, 0xffffff80, v41
	v_bitop3_b32 v41, v41, s38, v174 bitop3:0x36
	v_cndmask_b32_e32 v25, v65, v64, vcc
	v_not_b32_e32 v64, v9
	v_or_b32_e32 v65, 0x80000000, v9
	v_cmp_gt_i32_e32 vcc, 0, v9
	v_and_b32_e32 v25, 0xffffff80, v25
	v_bitop3_b32 v25, v25, 63, v174 bitop3:0x36
	v_cndmask_b32_e32 v9, v65, v64, vcc
	v_not_b32_e32 v64, v58
	v_or_b32_e32 v65, 0x80000000, v58
	v_cmp_gt_i32_e32 vcc, 0, v58
	v_and_b32_e32 v9, 0xffffff80, v9
	v_bitop3_b32 v9, v9, 31, v174 bitop3:0x36
	v_cndmask_b32_e32 v58, v65, v64, vcc
	v_not_b32_e32 v64, v42
	v_or_b32_e32 v65, 0x80000000, v42
	v_cmp_gt_i32_e32 vcc, 0, v42
	v_and_b32_e32 v58, 0xffffff80, v58
	v_bitop3_b32 v58, v58, s39, v175 bitop3:0x36
	v_cndmask_b32_e32 v42, v65, v64, vcc
	v_not_b32_e32 v64, v26
	v_or_b32_e32 v65, 0x80000000, v26
	v_cmp_gt_i32_e32 vcc, 0, v26
	v_and_b32_e32 v42, 0xffffff80, v42
	v_bitop3_b32 v42, v42, s38, v175 bitop3:0x36
	v_cndmask_b32_e32 v26, v65, v64, vcc
	v_not_b32_e32 v64, v10
	v_or_b32_e32 v65, 0x80000000, v10
	v_cmp_gt_i32_e32 vcc, 0, v10
	v_and_b32_e32 v26, 0xffffff80, v26
	v_bitop3_b32 v26, v26, 63, v175 bitop3:0x36
	v_cndmask_b32_e32 v10, v65, v64, vcc
	v_not_b32_e32 v64, v59
	v_or_b32_e32 v65, 0x80000000, v59
	v_cmp_gt_i32_e32 vcc, 0, v59
	v_and_b32_e32 v10, 0xffffff80, v10
	v_bitop3_b32 v10, v10, 31, v175 bitop3:0x36
	v_cndmask_b32_e32 v59, v65, v64, vcc
	v_not_b32_e32 v64, v43
	v_or_b32_e32 v65, 0x80000000, v43
	v_cmp_gt_i32_e32 vcc, 0, v43
	v_and_b32_e32 v59, 0xffffff80, v59
	v_bitop3_b32 v59, v59, s39, v179 bitop3:0x36
	v_cndmask_b32_e32 v43, v65, v64, vcc
	v_not_b32_e32 v64, v27
	v_or_b32_e32 v65, 0x80000000, v27
	v_cmp_gt_i32_e32 vcc, 0, v27
	v_and_b32_e32 v43, 0xffffff80, v43
	v_bitop3_b32 v43, v43, s38, v179 bitop3:0x36
	v_cndmask_b32_e32 v27, v65, v64, vcc
	v_not_b32_e32 v64, v11
	v_or_b32_e32 v65, 0x80000000, v11
	v_cmp_gt_i32_e32 vcc, 0, v11
	v_and_b32_e32 v27, 0xffffff80, v27
	v_bitop3_b32 v27, v27, 63, v179 bitop3:0x36
	v_cndmask_b32_e32 v11, v65, v64, vcc
	v_not_b32_e32 v64, v60
	v_or_b32_e32 v65, 0x80000000, v60
	v_cmp_gt_i32_e32 vcc, 0, v60
	v_and_b32_e32 v11, 0xffffff80, v11
	v_bitop3_b32 v11, v11, 31, v179 bitop3:0x36
	v_cndmask_b32_e32 v60, v65, v64, vcc
	v_not_b32_e32 v64, v44
	v_or_b32_e32 v65, 0x80000000, v44
	v_cmp_gt_i32_e32 vcc, 0, v44
	v_and_b32_e32 v60, 0xffffff80, v60
	v_bitop3_b32 v60, v60, s39, v170 bitop3:0x36
	v_cndmask_b32_e32 v44, v65, v64, vcc
	v_not_b32_e32 v64, v28
	v_or_b32_e32 v65, 0x80000000, v28
	v_cmp_gt_i32_e32 vcc, 0, v28
	v_and_b32_e32 v44, 0xffffff80, v44
	v_bitop3_b32 v44, v44, s38, v170 bitop3:0x36
	v_cndmask_b32_e32 v28, v65, v64, vcc
	v_not_b32_e32 v64, v12
	v_or_b32_e32 v65, 0x80000000, v12
	v_cmp_gt_i32_e32 vcc, 0, v12
	v_and_b32_e32 v28, 0xffffff80, v28
	v_bitop3_b32 v28, v28, 63, v170 bitop3:0x36
	v_cndmask_b32_e32 v12, v65, v64, vcc
	v_not_b32_e32 v64, v61
	v_or_b32_e32 v65, 0x80000000, v61
	v_cmp_gt_i32_e32 vcc, 0, v61
	v_and_b32_e32 v12, 0xffffff80, v12
	v_bitop3_b32 v12, v12, 31, v170 bitop3:0x36
	v_cndmask_b32_e32 v61, v65, v64, vcc
	v_not_b32_e32 v64, v45
	v_or_b32_e32 v65, 0x80000000, v45
	v_cmp_gt_i32_e32 vcc, 0, v45
	v_and_b32_e32 v61, 0xffffff80, v61
	v_bitop3_b32 v61, v61, s39, v180 bitop3:0x36
	v_cndmask_b32_e32 v45, v65, v64, vcc
	v_not_b32_e32 v64, v29
	v_or_b32_e32 v65, 0x80000000, v29
	v_cmp_gt_i32_e32 vcc, 0, v29
; DEV unsigned fkey(float v) { const unsigned u = __float_as_uint(v); return (u & 0x80000000u) ? ~u : (u | 0x80000000u); }
; DEV void sort16_desc(unsigned (&x)[16]) {
; #pragma unroll
;   for (int k = 2; k <= 16; k <<= 1)
; #pragma unroll
;     for (int j = k >> 1; j > 0; j >>= 1)
; #pragma unroll
;       for (int i = 0; i < 16; ++i) {
;         const int p = i ^ j;
;         if (p > i) {
;           if ((i & k) == 0) { TK_CE(x[i], x[p]); } else { TK_CE(x[p], x[i]); }
;         }
;       }
; }
; __device__ void peer_q_topk_item(const Params& P, int l, int item, char* smem) {
;     ...
;       for (int i = 0; i < 16; ++i) {
;         const int kb0 = (i & 3) + 8 * (i >> 2) + 4 * hk;
;         Lc[i] = (fkey(sa[0][i]) & ~0x7Fu) | (unsigned)(127 - kb0);
;         G1[i] = (fkey(sa[1][i]) & ~0x7Fu) | (unsigned)(127 - (32 + kb0));
;         G2[i] = (fkey(sa[2][i]) & ~0x7Fu) | (unsigned)(127 - (64 + kb0));
;         G3[i] = (fkey(sa[3][i]) & ~0x7Fu) | (unsigned)(127 - (96 + kb0));
;       }
;       sort16_desc(Lc); sort16_desc(G1); sort16_desc(G2); sort16_desc(G3);
	v_and_b32_e32 v45, 0xffffff80, v45
	v_bitop3_b32 v45, v45, s38, v180 bitop3:0x36
	v_cndmask_b32_e32 v29, v65, v64, vcc
	v_not_b32_e32 v64, v13
	v_or_b32_e32 v65, 0x80000000, v13
	v_cmp_gt_i32_e32 vcc, 0, v13
	v_and_b32_e32 v29, 0xffffff80, v29
	v_bitop3_b32 v29, v29, 63, v180 bitop3:0x36
	v_cndmask_b32_e32 v13, v65, v64, vcc
	v_not_b32_e32 v64, v62
	v_or_b32_e32 v65, 0x80000000, v62
	v_cmp_gt_i32_e32 vcc, 0, v62
	v_and_b32_e32 v13, 0xffffff80, v13
	v_bitop3_b32 v13, v13, 31, v180 bitop3:0x36
	v_cndmask_b32_e32 v62, v65, v64, vcc
	v_not_b32_e32 v64, v46
	v_or_b32_e32 v65, 0x80000000, v46
	v_cmp_gt_i32_e32 vcc, 0, v46
	v_and_b32_e32 v62, 0xffffff80, v62
	v_bitop3_b32 v62, v62, s39, v181 bitop3:0x36
	v_cndmask_b32_e32 v46, v65, v64, vcc
	v_not_b32_e32 v64, v30
	v_or_b32_e32 v65, 0x80000000, v30
	v_cmp_gt_i32_e32 vcc, 0, v30
	v_and_b32_e32 v46, 0xffffff80, v46
	v_bitop3_b32 v46, v46, s38, v181 bitop3:0x36
	v_cndmask_b32_e32 v30, v65, v64, vcc
	v_not_b32_e32 v64, v14
	v_or_b32_e32 v65, 0x80000000, v14
	v_cmp_gt_i32_e32 vcc, 0, v14
	v_and_b32_e32 v30, 0xffffff80, v30
	v_bitop3_b32 v30, v30, 63, v181 bitop3:0x36
	v_cndmask_b32_e32 v14, v65, v64, vcc
	v_not_b32_e32 v64, v63
	v_or_b32_e32 v65, 0x80000000, v63
	v_cmp_gt_i32_e32 vcc, 0, v63
	v_and_b32_e32 v14, 0xffffff80, v14
	v_bitop3_b32 v14, v14, 31, v181 bitop3:0x36
	v_cndmask_b32_e32 v63, v65, v64, vcc
	v_not_b32_e32 v64, v47
	v_or_b32_e32 v65, 0x80000000, v47
	v_cmp_gt_i32_e32 vcc, 0, v47
	v_and_b32_e32 v63, 0xffffff80, v63
	v_bitop3_b32 v63, v63, s39, v182 bitop3:0x36
	v_cndmask_b32_e32 v47, v65, v64, vcc
	v_not_b32_e32 v64, v31
	v_or_b32_e32 v65, 0x80000000, v31
	v_cmp_gt_i32_e32 vcc, 0, v31
	v_and_b32_e32 v47, 0xffffff80, v47
	v_bitop3_b32 v47, v47, s38, v182 bitop3:0x36
	v_cndmask_b32_e32 v31, v65, v64, vcc
	v_not_b32_e32 v64, v15
	v_or_b32_e32 v65, 0x80000000, v15
	v_cmp_gt_i32_e32 vcc, 0, v15
	v_and_b32_e32 v31, 0xffffff80, v31
	v_bitop3_b32 v31, v31, 63, v182 bitop3:0x36
	v_cndmask_b32_e32 v15, v65, v64, vcc
	v_and_b32_e32 v15, 0xffffff80, v15
	v_bitop3_b32 v15, v15, 31, v182 bitop3:0x36
	v_max_u32_e32 v64, v48, v49
	v_min_u32_e32 v48, v48, v49
	v_max_u32_e32 v49, v51, v50
	v_min_u32_e32 v50, v51, v50
	v_max_u32_e32 v51, v52, v53
	v_min_u32_e32 v52, v52, v53
	v_max_u32_e32 v53, v55, v54
	v_min_u32_e32 v54, v55, v54
	v_max_u32_e32 v55, v56, v57
	v_min_u32_e32 v56, v56, v57
	v_max_u32_e32 v57, v59, v58
	v_min_u32_e32 v58, v59, v58
	v_max_u32_e32 v59, v60, v61
	v_min_u32_e32 v60, v60, v61
	v_max_u32_e32 v61, v63, v62
	v_min_u32_e32 v62, v63, v62
	v_max_u32_e32 v72, v32, v33
	v_min_u32_e32 v32, v32, v33
	v_max_u32_e32 v33, v35, v34
	v_min_u32_e32 v34, v35, v34
	v_max_u32_e32 v35, v36, v37
	v_min_u32_e32 v36, v36, v37
	v_max_u32_e32 v37, v39, v38
	v_min_u32_e32 v38, v39, v38
	v_max_u32_e32 v39, v40, v41
	v_min_u32_e32 v40, v40, v41
	v_max_u32_e32 v41, v43, v42
	v_min_u32_e32 v42, v43, v42
	v_max_u32_e32 v43, v44, v45
	v_min_u32_e32 v44, v44, v45
	v_max_u32_e32 v45, v47, v46
	v_min_u32_e32 v46, v47, v46
	v_max_u32_e32 v80, v16, v17
	v_min_u32_e32 v16, v16, v17
	v_max_u32_e32 v17, v19, v18
	v_min_u32_e32 v18, v19, v18
	v_max_u32_e32 v19, v20, v21
	v_min_u32_e32 v20, v20, v21
	v_max_u32_e32 v21, v23, v22
	v_min_u32_e32 v22, v23, v22
	v_max_u32_e32 v23, v24, v25
	v_min_u32_e32 v24, v24, v25
	v_max_u32_e32 v25, v27, v26
	v_min_u32_e32 v26, v27, v26
	v_max_u32_e32 v27, v28, v29
	v_min_u32_e32 v28, v28, v29
	v_max_u32_e32 v29, v31, v30
	v_min_u32_e32 v30, v31, v30
	v_max_u32_e32 v88, v0, v1
	v_min_u32_e32 v0, v0, v1
	v_max_u32_e32 v1, v3, v2
	v_min_u32_e32 v2, v3, v2
	v_max_u32_e32 v3, v4, v5
	v_min_u32_e32 v4, v4, v5
	v_max_u32_e32 v5, v7, v6
	v_min_u32_e32 v6, v7, v6
	v_max_u32_e32 v7, v8, v9
	v_min_u32_e32 v8, v8, v9
	v_max_u32_e32 v9, v11, v10
	v_min_u32_e32 v10, v11, v10
	v_max_u32_e32 v11, v12, v13
	v_min_u32_e32 v12, v12, v13
	v_max_u32_e32 v13, v15, v14
	v_min_u32_e32 v14, v15, v14
	v_max_u32_e32 v63, v64, v50
	v_min_u32_e32 v50, v64, v50
	v_max_u32_e32 v64, v48, v49
	v_min_u32_e32 v48, v48, v49
	v_max_u32_e32 v49, v54, v51
	v_min_u32_e32 v51, v54, v51
	v_max_u32_e32 v54, v53, v52
	v_min_u32_e32 v52, v53, v52
	v_max_u32_e32 v53, v55, v58
	v_min_u32_e32 v55, v55, v58
	v_max_u32_e32 v58, v56, v57
	v_min_u32_e32 v56, v56, v57
	v_max_u32_e32 v57, v62, v59
	v_min_u32_e32 v59, v62, v59
	v_max_u32_e32 v62, v61, v60
	v_min_u32_e32 v60, v61, v60
	v_max_u32_e32 v47, v72, v34
	v_min_u32_e32 v34, v72, v34
	v_max_u32_e32 v72, v32, v33
	v_min_u32_e32 v32, v32, v33
	v_max_u32_e32 v33, v38, v35
	v_min_u32_e32 v35, v38, v35
	v_max_u32_e32 v38, v37, v36
	v_min_u32_e32 v36, v37, v36
	v_max_u32_e32 v37, v39, v42
	v_min_u32_e32 v39, v39, v42
	v_max_u32_e32 v42, v40, v41
	v_min_u32_e32 v40, v40, v41
	v_max_u32_e32 v41, v46, v43
	v_min_u32_e32 v43, v46, v43
	v_max_u32_e32 v46, v45, v44
	v_min_u32_e32 v44, v45, v44
	v_max_u32_e32 v31, v80, v18
	v_min_u32_e32 v18, v80, v18
	v_max_u32_e32 v80, v16, v17
	v_min_u32_e32 v16, v16, v17
	v_max_u32_e32 v17, v22, v19
	v_min_u32_e32 v19, v22, v19
	v_max_u32_e32 v22, v21, v20
	v_min_u32_e32 v20, v21, v20
	v_max_u32_e32 v21, v23, v26
	v_min_u32_e32 v23, v23, v26
	v_max_u32_e32 v26, v24, v25
	v_min_u32_e32 v24, v24, v25
	v_max_u32_e32 v25, v30, v27
	v_min_u32_e32 v27, v30, v27
	v_max_u32_e32 v30, v29, v28
	v_min_u32_e32 v28, v29, v28
	v_max_u32_e32 v15, v88, v2
	v_min_u32_e32 v2, v88, v2
	v_max_u32_e32 v88, v0, v1
	v_min_u32_e32 v0, v0, v1
	v_max_u32_e32 v1, v6, v3
	v_min_u32_e32 v3, v6, v3
	v_max_u32_e32 v6, v5, v4
	v_min_u32_e32 v4, v5, v4
	v_max_u32_e32 v5, v7, v10
	v_min_u32_e32 v7, v7, v10
	v_max_u32_e32 v10, v8, v9
	v_min_u32_e32 v8, v8, v9
	v_max_u32_e32 v9, v14, v11
; DEV void sort16_desc(unsigned (&x)[16]) {
; #pragma unroll
;   for (int k = 2; k <= 16; k <<= 1)
; #pragma unroll
;     for (int j = k >> 1; j > 0; j >>= 1)
; #pragma unroll
;       for (int i = 0; i < 16; ++i) {
;         const int p = i ^ j;
;         if (p > i) {
;           if ((i & k) == 0) { TK_CE(x[i], x[p]); } else { TK_CE(x[p], x[i]); }
;         }
;       }
; }
	v_min_u32_e32 v11, v14, v11
	v_max_u32_e32 v14, v13, v12
	v_min_u32_e32 v12, v13, v12
	v_max_u32_e32 v61, v63, v64
	v_min_u32_e32 v63, v63, v64
	v_max_u32_e32 v64, v50, v48
	v_min_u32_e32 v48, v50, v48
	v_max_u32_e32 v50, v52, v51
	v_min_u32_e32 v51, v52, v51
	v_max_u32_e32 v52, v54, v49
	v_min_u32_e32 v49, v54, v49
	v_max_u32_e32 v54, v53, v58
	v_min_u32_e32 v53, v53, v58
	v_max_u32_e32 v58, v55, v56
	v_min_u32_e32 v55, v55, v56
	v_max_u32_e32 v56, v60, v59
	v_min_u32_e32 v59, v60, v59
	v_max_u32_e32 v60, v62, v57
	v_min_u32_e32 v57, v62, v57
	v_max_u32_e32 v45, v47, v72
	v_min_u32_e32 v47, v47, v72
	v_max_u32_e32 v72, v34, v32
	v_min_u32_e32 v32, v34, v32
	v_max_u32_e32 v34, v36, v35
	v_min_u32_e32 v35, v36, v35
	v_max_u32_e32 v36, v38, v33
	v_min_u32_e32 v33, v38, v33
	v_max_u32_e32 v38, v37, v42
	v_min_u32_e32 v37, v37, v42
	v_max_u32_e32 v42, v39, v40
	v_min_u32_e32 v39, v39, v40
	v_max_u32_e32 v40, v44, v43
	v_min_u32_e32 v43, v44, v43
	v_max_u32_e32 v44, v46, v41
	v_min_u32_e32 v41, v46, v41
	v_max_u32_e32 v29, v31, v80
	v_min_u32_e32 v31, v31, v80
	v_max_u32_e32 v80, v18, v16
	v_min_u32_e32 v16, v18, v16
	v_max_u32_e32 v18, v20, v19
	v_min_u32_e32 v19, v20, v19
	v_max_u32_e32 v20, v22, v17
	v_min_u32_e32 v17, v22, v17
	v_max_u32_e32 v22, v21, v26
	v_min_u32_e32 v21, v21, v26
	v_max_u32_e32 v26, v23, v24
	v_min_u32_e32 v23, v23, v24
	v_max_u32_e32 v24, v28, v27
	v_min_u32_e32 v27, v28, v27
	v_max_u32_e32 v28, v30, v25
	v_min_u32_e32 v25, v30, v25
	v_max_u32_e32 v13, v15, v88
	v_min_u32_e32 v15, v15, v88
	v_max_u32_e32 v88, v2, v0
	v_min_u32_e32 v0, v2, v0
	v_max_u32_e32 v2, v4, v3
	v_min_u32_e32 v3, v4, v3
	v_max_u32_e32 v4, v6, v1
	v_min_u32_e32 v1, v6, v1
	v_max_u32_e32 v6, v5, v10
	v_min_u32_e32 v5, v5, v10
	v_max_u32_e32 v10, v7, v8
	v_min_u32_e32 v7, v7, v8
	v_max_u32_e32 v8, v12, v11
	v_min_u32_e32 v11, v12, v11
	v_max_u32_e32 v12, v14, v9
	v_min_u32_e32 v9, v14, v9
	v_max_u32_e32 v62, v61, v51
	v_min_u32_e32 v51, v61, v51
	v_max_u32_e32 v61, v63, v50
	v_min_u32_e32 v50, v63, v50
	v_max_u32_e32 v63, v64, v49
	v_min_u32_e32 v49, v64, v49
	v_max_u32_e32 v64, v48, v52
	v_min_u32_e32 v48, v48, v52
	v_max_u32_e32 v52, v59, v54
	v_min_u32_e32 v54, v59, v54
	v_max_u32_e32 v59, v56, v53
	v_min_u32_e32 v53, v56, v53
	v_max_u32_e32 v56, v57, v58
	v_min_u32_e32 v57, v57, v58
	v_max_u32_e32 v58, v60, v55
	v_min_u32_e32 v55, v60, v55
	v_max_u32_e32 v46, v45, v35
	v_min_u32_e32 v35, v45, v35
	v_max_u32_e32 v45, v47, v34
	v_min_u32_e32 v34, v47, v34
	v_max_u32_e32 v47, v72, v33
	v_min_u32_e32 v33, v72, v33
	v_max_u32_e32 v72, v32, v36
	v_min_u32_e32 v32, v32, v36
	v_max_u32_e32 v36, v43, v38
	v_min_u32_e32 v38, v43, v38
	v_max_u32_e32 v43, v40, v37
	v_min_u32_e32 v37, v40, v37
	v_max_u32_e32 v40, v41, v42
	v_min_u32_e32 v41, v41, v42
	v_max_u32_e32 v42, v44, v39
	v_min_u32_e32 v39, v44, v39
	v_max_u32_e32 v30, v29, v19
	v_min_u32_e32 v19, v29, v19
	v_max_u32_e32 v29, v31, v18
	v_min_u32_e32 v18, v31, v18
	v_max_u32_e32 v31, v80, v17
	v_min_u32_e32 v17, v80, v17
	v_max_u32_e32 v80, v16, v20
	v_min_u32_e32 v16, v16, v20
	v_max_u32_e32 v20, v27, v22
	v_min_u32_e32 v22, v27, v22
	v_max_u32_e32 v27, v24, v21
	v_min_u32_e32 v21, v24, v21
	v_max_u32_e32 v24, v25, v26
	v_min_u32_e32 v25, v25, v26
	v_max_u32_e32 v26, v28, v23
	v_min_u32_e32 v23, v28, v23
	v_max_u32_e32 v14, v13, v3
	v_min_u32_e32 v3, v13, v3
	v_max_u32_e32 v13, v15, v2
	v_min_u32_e32 v2, v15, v2
	v_max_u32_e32 v15, v88, v1
	v_min_u32_e32 v1, v88, v1
	v_max_u32_e32 v88, v0, v4
	v_min_u32_e32 v0, v0, v4
	v_max_u32_e32 v4, v11, v6
	v_min_u32_e32 v6, v11, v6
	v_max_u32_e32 v11, v8, v5
	v_min_u32_e32 v5, v8, v5
	v_max_u32_e32 v8, v9, v10
	v_min_u32_e32 v9, v9, v10
	v_max_u32_e32 v10, v12, v7
	v_min_u32_e32 v7, v12, v7
	v_max_u32_e32 v60, v62, v63
	v_min_u32_e32 v62, v62, v63
	v_max_u32_e32 v63, v61, v64
	v_min_u32_e32 v61, v61, v64
	v_max_u32_e32 v64, v51, v49
	v_min_u32_e32 v49, v51, v49
	v_max_u32_e32 v51, v50, v48
	v_min_u32_e32 v48, v50, v48
	v_max_u32_e32 v50, v57, v54
	v_min_u32_e32 v54, v57, v54
	v_max_u32_e32 v57, v55, v53
	v_min_u32_e32 v53, v55, v53
	v_max_u32_e32 v55, v56, v52
	v_min_u32_e32 v52, v56, v52
	v_max_u32_e32 v56, v58, v59
	v_min_u32_e32 v58, v58, v59
	v_max_u32_e32 v44, v46, v47
	v_min_u32_e32 v46, v46, v47
	v_max_u32_e32 v47, v45, v72
	v_min_u32_e32 v45, v45, v72
	v_max_u32_e32 v72, v35, v33
	v_min_u32_e32 v33, v35, v33
	v_max_u32_e32 v35, v34, v32
	v_min_u32_e32 v32, v34, v32
	v_max_u32_e32 v34, v41, v38
	v_min_u32_e32 v38, v41, v38
	v_max_u32_e32 v41, v39, v37
	v_min_u32_e32 v37, v39, v37
	v_max_u32_e32 v39, v40, v36
	v_min_u32_e32 v36, v40, v36
	v_max_u32_e32 v40, v42, v43
	v_min_u32_e32 v42, v42, v43
	v_max_u32_e32 v28, v30, v31
	v_min_u32_e32 v30, v30, v31
	v_max_u32_e32 v31, v29, v80
	v_min_u32_e32 v29, v29, v80
	v_max_u32_e32 v80, v19, v17
	v_min_u32_e32 v17, v19, v17
	v_max_u32_e32 v19, v18, v16
	v_min_u32_e32 v16, v18, v16
	v_max_u32_e32 v18, v25, v22
	v_min_u32_e32 v22, v25, v22
	v_max_u32_e32 v25, v23, v21
	v_min_u32_e32 v21, v23, v21
	v_max_u32_e32 v23, v24, v20
	v_min_u32_e32 v20, v24, v20
	v_max_u32_e32 v24, v26, v27
	v_min_u32_e32 v26, v26, v27
	v_max_u32_e32 v12, v14, v15
	v_min_u32_e32 v14, v14, v15
	v_max_u32_e32 v15, v13, v88
	v_min_u32_e32 v13, v13, v88
	v_max_u32_e32 v88, v3, v1
	v_min_u32_e32 v1, v3, v1
	v_max_u32_e32 v3, v2, v0
	v_min_u32_e32 v0, v2, v0
	v_max_u32_e32 v2, v9, v6
	v_min_u32_e32 v6, v9, v6
	v_max_u32_e32 v9, v7, v5
	v_min_u32_e32 v5, v7, v5
	v_max_u32_e32 v7, v8, v4
	v_min_u32_e32 v4, v8, v4
	v_max_u32_e32 v8, v10, v11
	v_min_u32_e32 v10, v10, v11
	v_max_u32_e32 v59, v60, v63
	v_min_u32_e32 v60, v60, v63
	v_max_u32_e32 v63, v62, v61
; DEV void sort16_desc(unsigned (&x)[16]) {
; #pragma unroll
;   for (int k = 2; k <= 16; k <<= 1)
; #pragma unroll
;     for (int j = k >> 1; j > 0; j >>= 1)
; #pragma unroll
;       for (int i = 0; i < 16; ++i) {
;         const int p = i ^ j;
;         if (p > i) {
;           if ((i & k) == 0) { TK_CE(x[i], x[p]); } else { TK_CE(x[p], x[i]); }
;         }
;       }
; }
	v_min_u32_e32 v61, v62, v61
	v_max_u32_e32 v62, v64, v51
	v_min_u32_e32 v51, v64, v51
	v_max_u32_e32 v64, v49, v48
	v_min_u32_e32 v48, v49, v48
	v_max_u32_e32 v49, v53, v54
	v_min_u32_e32 v53, v53, v54
	v_max_u32_e32 v54, v57, v50
	v_min_u32_e32 v50, v57, v50
	v_max_u32_e32 v57, v58, v52
	v_min_u32_e32 v52, v58, v52
	v_max_u32_e32 v58, v56, v55
	v_min_u32_e32 v55, v56, v55
	v_max_u32_e32 v43, v44, v47
	v_min_u32_e32 v44, v44, v47
	v_max_u32_e32 v47, v46, v45
	v_min_u32_e32 v45, v46, v45
	v_max_u32_e32 v46, v72, v35
	v_min_u32_e32 v35, v72, v35
	v_max_u32_e32 v72, v33, v32
	v_min_u32_e32 v32, v33, v32
	v_max_u32_e32 v33, v37, v38
	v_min_u32_e32 v37, v37, v38
	v_max_u32_e32 v38, v41, v34
	v_min_u32_e32 v34, v41, v34
	v_max_u32_e32 v41, v42, v36
	v_min_u32_e32 v36, v42, v36
	v_max_u32_e32 v42, v40, v39
	v_min_u32_e32 v39, v40, v39
	v_max_u32_e32 v27, v28, v31
	v_min_u32_e32 v28, v28, v31
	v_max_u32_e32 v31, v30, v29
	v_min_u32_e32 v29, v30, v29
	v_max_u32_e32 v30, v80, v19
	v_min_u32_e32 v19, v80, v19
	v_max_u32_e32 v80, v17, v16
	v_min_u32_e32 v16, v17, v16
	v_max_u32_e32 v17, v21, v22
	v_min_u32_e32 v21, v21, v22
	v_max_u32_e32 v22, v25, v18
	v_min_u32_e32 v18, v25, v18
	v_max_u32_e32 v25, v26, v20
	v_min_u32_e32 v20, v26, v20
	v_max_u32_e32 v26, v24, v23
	v_min_u32_e32 v23, v24, v23
	v_max_u32_e32 v11, v12, v15
	v_min_u32_e32 v12, v12, v15
	v_max_u32_e32 v15, v14, v13
	v_min_u32_e32 v13, v14, v13
	v_max_u32_e32 v14, v88, v3
	v_min_u32_e32 v3, v88, v3
	v_max_u32_e32 v88, v1, v0
	v_min_u32_e32 v0, v1, v0
	v_max_u32_e32 v1, v5, v6
	v_min_u32_e32 v5, v5, v6
	v_max_u32_e32 v6, v9, v2
	v_min_u32_e32 v2, v9, v2
	v_max_u32_e32 v9, v10, v4
	v_min_u32_e32 v4, v10, v4
	v_max_u32_e32 v10, v8, v7
	v_min_u32_e32 v7, v8, v7
	v_max_u32_e32 v56, v59, v53
	v_min_u32_e32 v53, v59, v53
	v_max_u32_e32 v59, v60, v49
	v_min_u32_e32 v49, v60, v49
	v_max_u32_e32 v60, v63, v50
	v_min_u32_e32 v50, v63, v50
	v_max_u32_e32 v63, v61, v54
	v_min_u32_e32 v54, v61, v54
	v_max_u32_e32 v61, v62, v52
	v_min_u32_e32 v52, v62, v52
	v_max_u32_e32 v62, v51, v57
	v_min_u32_e32 v51, v51, v57
	v_max_u32_e32 v57, v64, v55
	v_min_u32_e32 v55, v64, v55
	v_max_u32_e32 v64, v48, v58
	v_min_u32_e32 v48, v48, v58
	v_max_u32_e32 v40, v43, v37
	v_min_u32_e32 v37, v43, v37
	v_max_u32_e32 v43, v44, v33
	v_min_u32_e32 v33, v44, v33
	v_max_u32_e32 v44, v47, v34
	v_min_u32_e32 v34, v47, v34
	v_max_u32_e32 v47, v45, v38
	v_min_u32_e32 v38, v45, v38
	v_max_u32_e32 v45, v46, v36
	v_min_u32_e32 v36, v46, v36
	v_max_u32_e32 v46, v35, v41
	v_min_u32_e32 v35, v35, v41
	v_max_u32_e32 v41, v72, v39
	v_min_u32_e32 v39, v72, v39
	v_max_u32_e32 v72, v32, v42
	v_min_u32_e32 v32, v32, v42
	v_max_u32_e32 v24, v27, v21
	v_min_u32_e32 v21, v27, v21
	v_max_u32_e32 v27, v28, v17
	v_min_u32_e32 v17, v28, v17
	v_max_u32_e32 v28, v31, v18
	v_min_u32_e32 v18, v31, v18
	v_max_u32_e32 v31, v29, v22
	v_min_u32_e32 v22, v29, v22
	v_max_u32_e32 v29, v30, v20
	v_min_u32_e32 v20, v30, v20
	v_max_u32_e32 v30, v19, v25
	v_min_u32_e32 v19, v19, v25
	v_max_u32_e32 v25, v80, v23
	v_min_u32_e32 v23, v80, v23
	v_max_u32_e32 v80, v16, v26
	v_min_u32_e32 v16, v16, v26
	v_max_u32_e32 v8, v11, v5
	v_min_u32_e32 v5, v11, v5
	v_max_u32_e32 v11, v12, v1
	v_min_u32_e32 v1, v12, v1
	v_max_u32_e32 v12, v15, v2
	v_min_u32_e32 v2, v15, v2
	v_max_u32_e32 v15, v13, v6
	v_min_u32_e32 v6, v13, v6
	v_max_u32_e32 v13, v14, v4
	v_min_u32_e32 v4, v14, v4
	v_max_u32_e32 v14, v3, v9
	v_min_u32_e32 v3, v3, v9
	v_max_u32_e32 v9, v88, v7
	v_min_u32_e32 v7, v88, v7
	v_max_u32_e32 v88, v0, v10
	v_min_u32_e32 v0, v0, v10
	v_max_u32_e32 v58, v56, v61
	v_min_u32_e32 v56, v56, v61
	v_max_u32_e32 v61, v59, v62
	v_min_u32_e32 v59, v59, v62
	v_max_u32_e32 v62, v60, v57
	v_min_u32_e32 v57, v60, v57
	v_max_u32_e32 v60, v63, v64
	v_min_u32_e32 v63, v63, v64
	v_max_u32_e32 v64, v53, v52
	v_min_u32_e32 v52, v53, v52
	v_max_u32_e32 v53, v49, v51
	v_min_u32_e32 v49, v49, v51
	v_max_u32_e32 v51, v50, v55
	v_min_u32_e32 v50, v50, v55
	v_max_u32_e32 v55, v54, v48
	v_min_u32_e32 v48, v54, v48
	v_max_u32_e32 v42, v40, v45
	v_min_u32_e32 v40, v40, v45
	v_max_u32_e32 v45, v43, v46
	v_min_u32_e32 v43, v43, v46
	v_max_u32_e32 v46, v44, v41
	v_min_u32_e32 v41, v44, v41
	v_max_u32_e32 v44, v47, v72
	v_min_u32_e32 v47, v47, v72
	v_max_u32_e32 v72, v37, v36
	v_min_u32_e32 v36, v37, v36
	v_max_u32_e32 v37, v33, v35
	v_min_u32_e32 v33, v33, v35
	v_max_u32_e32 v35, v34, v39
	v_min_u32_e32 v34, v34, v39
	v_max_u32_e32 v39, v38, v32
	v_min_u32_e32 v32, v38, v32
	v_max_u32_e32 v26, v24, v29
	v_min_u32_e32 v24, v24, v29
	v_max_u32_e32 v29, v27, v30
	v_min_u32_e32 v27, v27, v30
	v_max_u32_e32 v30, v28, v25
	v_min_u32_e32 v25, v28, v25
	v_max_u32_e32 v28, v31, v80
	v_min_u32_e32 v31, v31, v80
	v_max_u32_e32 v80, v21, v20
	v_min_u32_e32 v20, v21, v20
	v_max_u32_e32 v21, v17, v19
	v_min_u32_e32 v17, v17, v19
	v_max_u32_e32 v19, v18, v23
	v_min_u32_e32 v18, v18, v23
	v_max_u32_e32 v23, v22, v16
	v_min_u32_e32 v16, v22, v16
	v_max_u32_e32 v10, v8, v13
	v_min_u32_e32 v8, v8, v13
	v_max_u32_e32 v13, v11, v14
	v_min_u32_e32 v11, v11, v14
	v_max_u32_e32 v14, v12, v9
	v_min_u32_e32 v9, v12, v9
	v_max_u32_e32 v12, v15, v88
	v_min_u32_e32 v15, v15, v88
	v_max_u32_e32 v88, v5, v4
	v_min_u32_e32 v4, v5, v4
	v_max_u32_e32 v5, v1, v3
	v_min_u32_e32 v1, v1, v3
	v_max_u32_e32 v3, v2, v7
	v_min_u32_e32 v2, v2, v7
	v_max_u32_e32 v7, v6, v0
	v_min_u32_e32 v0, v6, v0
	v_max_u32_e32 v54, v58, v62
	v_min_u32_e32 v58, v58, v62
	v_max_u32_e32 v62, v61, v60
	v_min_u32_e32 v60, v61, v60
	v_max_u32_e32 v61, v56, v57
	v_min_u32_e32 v56, v56, v57
	v_max_u32_e32 v57, v59, v63
	v_min_u32_e32 v59, v59, v63
; DEV void sort16_desc(unsigned (&x)[16]) {
; #pragma unroll
;   for (int k = 2; k <= 16; k <<= 1)
; #pragma unroll
;     for (int j = k >> 1; j > 0; j >>= 1)
; #pragma unroll
;       for (int i = 0; i < 16; ++i) {
;         const int p = i ^ j;
;         if (p > i) {
;           if ((i & k) == 0) { TK_CE(x[i], x[p]); } else { TK_CE(x[p], x[i]); }
;         }
;       }
; }
; DEV void merge_top16(unsigned (&x)[16], const unsigned (&y)[16]) {
; #pragma unroll
;   for (int i = 0; i < 16; ++i) x[i] = max(x[i], y[15 - i]);
; #pragma unroll
;   for (int j = 8; j > 0; j >>= 1)
; #pragma unroll
;     for (int i = 0; i < 16; ++i) {
;       const int p = i ^ j;
;       if (p > i) { TK_CE(x[i], x[p]); }
;     }
; }
	v_max_u32_e32 v63, v64, v51
	v_min_u32_e32 v51, v64, v51
	v_max_u32_e32 v64, v53, v55
	v_min_u32_e32 v53, v53, v55
	v_max_u32_e32 v55, v52, v50
	v_min_u32_e32 v50, v52, v50
	v_max_u32_e32 v52, v49, v48
	v_min_u32_e32 v48, v49, v48
	v_max_u32_e32 v38, v42, v46
	v_min_u32_e32 v42, v42, v46
	v_max_u32_e32 v46, v45, v44
	v_min_u32_e32 v44, v45, v44
	v_max_u32_e32 v45, v40, v41
	v_min_u32_e32 v40, v40, v41
	v_max_u32_e32 v41, v43, v47
	v_min_u32_e32 v43, v43, v47
	v_max_u32_e32 v47, v72, v35
	v_min_u32_e32 v35, v72, v35
	v_max_u32_e32 v72, v37, v39
	v_min_u32_e32 v37, v37, v39
	v_max_u32_e32 v39, v36, v34
	v_min_u32_e32 v34, v36, v34
	v_max_u32_e32 v36, v33, v32
	v_min_u32_e32 v32, v33, v32
	v_max_u32_e32 v22, v26, v30
	v_min_u32_e32 v26, v26, v30
	v_max_u32_e32 v30, v29, v28
	v_min_u32_e32 v28, v29, v28
	v_max_u32_e32 v29, v24, v25
	v_min_u32_e32 v24, v24, v25
	v_max_u32_e32 v25, v27, v31
	v_min_u32_e32 v27, v27, v31
	v_max_u32_e32 v31, v80, v19
	v_min_u32_e32 v19, v80, v19
	v_max_u32_e32 v80, v21, v23
	v_min_u32_e32 v21, v21, v23
	v_max_u32_e32 v23, v20, v18
	v_min_u32_e32 v18, v20, v18
	v_max_u32_e32 v20, v17, v16
	v_min_u32_e32 v16, v17, v16
	v_max_u32_e32 v6, v10, v14
	v_min_u32_e32 v10, v10, v14
	v_max_u32_e32 v14, v13, v12
	v_min_u32_e32 v12, v13, v12
	v_max_u32_e32 v13, v8, v9
	v_min_u32_e32 v8, v8, v9
	v_max_u32_e32 v9, v11, v15
	v_min_u32_e32 v11, v11, v15
	v_max_u32_e32 v15, v88, v3
	v_min_u32_e32 v3, v88, v3
	v_max_u32_e32 v88, v5, v7
	v_min_u32_e32 v5, v5, v7
	v_max_u32_e32 v7, v4, v2
	v_min_u32_e32 v2, v4, v2
	v_max_u32_e32 v4, v1, v0
	v_min_u32_e32 v0, v1, v0
	v_min_u32_e32 v49, v54, v62
	v_min_u32_e32 v65, v58, v60
	v_min_u32_e32 v66, v61, v57
	v_min_u32_e32 v67, v56, v59
	v_min_u32_e32 v68, v63, v64
	v_min_u32_e32 v69, v51, v53
	v_min_u32_e32 v70, v55, v52
	v_min_u32_e32 v71, v50, v48
	v_min_u32_e32 v33, v38, v46
	v_min_u32_e32 v73, v42, v44
	v_min_u32_e32 v74, v45, v41
	v_min_u32_e32 v75, v40, v43
	v_min_u32_e32 v76, v47, v72
	v_min_u32_e32 v77, v35, v37
	v_min_u32_e32 v78, v39, v36
	v_min_u32_e32 v79, v34, v32
	v_min_u32_e32 v17, v22, v30
	v_min_u32_e32 v81, v26, v28
	v_min_u32_e32 v82, v29, v25
	v_min_u32_e32 v83, v24, v27
	v_min_u32_e32 v84, v31, v80
	v_min_u32_e32 v85, v19, v21
	v_min_u32_e32 v86, v23, v20
	v_min_u32_e32 v87, v18, v16
	v_min_u32_e32 v1, v6, v14
	v_min_u32_e32 v89, v10, v12
	v_min_u32_e32 v90, v13, v9
	v_min_u32_e32 v91, v8, v11
	v_min_u32_e32 v92, v15, v88
	v_min_u32_e32 v93, v3, v5
	v_min_u32_e32 v94, v7, v4
	v_min_u32_e32 v95, v2, v0
	v_max3_u32 v54, v54, v62, v79
	v_max3_u32 v32, v49, v34, v32
	v_max3_u32 v34, v58, v60, v78
	v_max3_u32 v36, v65, v39, v36
	v_max3_u32 v39, v61, v57, v77
	v_max3_u32 v35, v66, v35, v37
	v_max3_u32 v37, v56, v59, v76
	v_max3_u32 v47, v67, v47, v72
	v_max3_u32 v49, v63, v64, v75
	v_max3_u32 v40, v68, v40, v43
	v_max3_u32 v43, v51, v53, v74
	v_max3_u32 v41, v69, v45, v41
	v_max3_u32 v45, v55, v52, v73
	v_max3_u32 v42, v70, v42, v44
	v_max3_u32 v33, v50, v48, v33
	v_max3_u32 v38, v71, v38, v46
	v_max3_u32 v22, v22, v30, v95
	v_max3_u32 v0, v17, v2, v0
	v_max3_u32 v2, v26, v28, v94
	v_max3_u32 v4, v81, v7, v4
	v_max3_u32 v7, v29, v25, v93
	v_max3_u32 v3, v82, v3, v5
	v_max3_u32 v5, v24, v27, v92
	v_max3_u32 v15, v83, v15, v88
	v_max3_u32 v17, v31, v80, v91
	v_max3_u32 v8, v84, v8, v11
	v_max3_u32 v11, v19, v21, v90
	v_max3_u32 v9, v85, v13, v9
	v_max3_u32 v13, v23, v20, v89
	v_max3_u32 v10, v86, v10, v12
	v_max3_u32 v1, v18, v16, v1
	v_max3_u32 v6, v87, v6, v14
	v_max_u32_e32 v44, v54, v49
	v_min_u32_e32 v46, v54, v49
	v_max_u32_e32 v48, v32, v40
	v_min_u32_e32 v32, v32, v40
	v_max_u32_e32 v40, v34, v43
	v_min_u32_e32 v34, v34, v43
	v_max_u32_e32 v43, v36, v41
	v_min_u32_e32 v36, v36, v41
	v_max_u32_e32 v41, v39, v45
	v_min_u32_e32 v39, v39, v45
	v_max_u32_e32 v45, v35, v42
	v_min_u32_e32 v35, v35, v42
	v_max_u32_e32 v42, v37, v33
	v_min_u32_e32 v33, v37, v33
	v_max_u32_e32 v37, v47, v38
	v_min_u32_e32 v38, v47, v38
	v_max_u32_e32 v12, v22, v17
	v_min_u32_e32 v14, v22, v17
	v_max_u32_e32 v16, v0, v8
	v_min_u32_e32 v0, v0, v8
	v_max_u32_e32 v8, v2, v11
	v_min_u32_e32 v2, v2, v11
	v_max_u32_e32 v11, v4, v9
	v_min_u32_e32 v4, v4, v9
	v_max_u32_e32 v9, v7, v13
	v_min_u32_e32 v7, v7, v13
	v_max_u32_e32 v13, v3, v10
	v_min_u32_e32 v3, v3, v10
	v_max_u32_e32 v10, v5, v1
	v_min_u32_e32 v1, v5, v1
	v_max_u32_e32 v5, v15, v6
	v_min_u32_e32 v6, v15, v6
	v_max_u32_e32 v47, v44, v41
	v_min_u32_e32 v41, v44, v41
	v_max_u32_e32 v44, v48, v45
	v_min_u32_e32 v45, v48, v45
	v_max_u32_e32 v48, v40, v42
	v_min_u32_e32 v40, v40, v42
	v_max_u32_e32 v42, v43, v37
	v_min_u32_e32 v37, v43, v37
	v_max_u32_e32 v43, v46, v39
	v_min_u32_e32 v39, v46, v39
	v_max_u32_e32 v46, v32, v35
	v_min_u32_e32 v32, v32, v35
	v_max_u32_e32 v35, v34, v33
	v_min_u32_e32 v33, v34, v33
	v_max_u32_e32 v34, v36, v38
	v_min_u32_e32 v36, v36, v38
	v_max_u32_e32 v15, v12, v9
	v_min_u32_e32 v9, v12, v9
	v_max_u32_e32 v12, v16, v13
	v_min_u32_e32 v13, v16, v13
	v_max_u32_e32 v16, v8, v10
	v_min_u32_e32 v8, v8, v10
	v_max_u32_e32 v10, v11, v5
	v_min_u32_e32 v5, v11, v5
	v_max_u32_e32 v11, v14, v7
	v_min_u32_e32 v7, v14, v7
	v_max_u32_e32 v14, v0, v3
	v_min_u32_e32 v0, v0, v3
	v_max_u32_e32 v3, v2, v1
	v_min_u32_e32 v1, v2, v1
	v_max_u32_e32 v2, v4, v6
	v_min_u32_e32 v4, v4, v6
	v_max_u32_e32 v38, v47, v48
	v_min_u32_e32 v47, v47, v48
	v_max_u32_e32 v48, v44, v42
	v_min_u32_e32 v42, v44, v42
	v_max_u32_e32 v44, v41, v40
	v_min_u32_e32 v40, v41, v40
	v_max_u32_e32 v41, v45, v37
	v_min_u32_e32 v37, v45, v37
	v_max_u32_e32 v45, v43, v35
	v_min_u32_e32 v35, v43, v35
	v_max_u32_e32 v43, v46, v34
	v_min_u32_e32 v34, v46, v34
; DEV unsigned xor32_u(unsigned v) { return (unsigned)__shfl_xor((int)v, 32, 64); }
; __device__ void peer_q_topk_item(const Params& P, int l, int item, char* smem) {
;     ...
;       merge_top16(Lc, G1); merge_top16(G2, G3); merge_top16(Lc, G2);
;     }
;     {
;       unsigned oth[16];
; #pragma unroll
;       for (int i = 0; i < 16; ++i) oth[i] = xor32_u(Lc[i]);
;       merge_top16(Lc, oth);
;     }
; #pragma unroll
;     for (int i = 0; i < 16; ++i) { L0[i] = L1[i]; L1[i] = Lc[i]; }
	v_max_u32_e32 v46, v39, v33
	v_min_u32_e32 v33, v39, v33
	v_max_u32_e32 v39, v32, v36
	v_min_u32_e32 v32, v32, v36
	v_max_u32_e32 v6, v15, v16
	v_min_u32_e32 v15, v15, v16
	v_max_u32_e32 v16, v12, v10
	v_min_u32_e32 v10, v12, v10
	v_max_u32_e32 v12, v9, v8
	v_min_u32_e32 v8, v9, v8
	v_max_u32_e32 v9, v13, v5
	v_min_u32_e32 v5, v13, v5
	v_max_u32_e32 v13, v11, v3
	v_min_u32_e32 v3, v11, v3
	v_max_u32_e32 v11, v14, v2
	v_min_u32_e32 v2, v14, v2
	v_max_u32_e32 v14, v7, v1
	v_min_u32_e32 v1, v7, v1
	v_max_u32_e32 v7, v0, v4
	v_min_u32_e32 v0, v0, v4
	v_min_u32_e32 v36, v38, v48
	v_min_u32_e32 v49, v47, v42
	v_min_u32_e32 v50, v44, v41
	v_min_u32_e32 v51, v40, v37
	v_min_u32_e32 v52, v45, v43
	v_min_u32_e32 v53, v35, v34
	v_min_u32_e32 v54, v46, v39
	v_min_u32_e32 v55, v33, v32
	v_min_u32_e32 v4, v6, v16
	v_min_u32_e32 v17, v15, v10
	v_min_u32_e32 v18, v12, v9
	v_min_u32_e32 v19, v8, v5
	v_min_u32_e32 v20, v13, v11
	v_min_u32_e32 v21, v3, v2
	v_min_u32_e32 v22, v14, v7
	v_min_u32_e32 v23, v1, v0
	v_max3_u32 v23, v38, v48, v23
	v_max3_u32 v0, v36, v1, v0
	v_max3_u32 v1, v47, v42, v22
	v_max3_u32 v7, v49, v14, v7
	v_max3_u32 v14, v44, v41, v21
	v_max3_u32 v2, v50, v3, v2
	v_max3_u32 v3, v40, v37, v20
	v_max3_u32 v11, v51, v13, v11
	v_max3_u32 v13, v45, v43, v19
	v_max3_u32 v5, v52, v8, v5
	v_max3_u32 v8, v35, v34, v18
	v_max3_u32 v9, v53, v12, v9
	v_max3_u32 v12, v46, v39, v17
	v_max3_u32 v10, v54, v15, v10
	v_max3_u32 v4, v33, v32, v4
	v_max3_u32 v6, v55, v6, v16
	v_max_u32_e32 v15, v23, v13
	v_min_u32_e32 v13, v23, v13
	v_max_u32_e32 v16, v0, v5
	v_min_u32_e32 v0, v0, v5
	v_max_u32_e32 v5, v1, v8
	v_min_u32_e32 v1, v1, v8
	v_max_u32_e32 v8, v7, v9
	v_min_u32_e32 v7, v7, v9
	v_max_u32_e32 v9, v14, v12
	v_min_u32_e32 v12, v14, v12
	v_max_u32_e32 v14, v2, v10
	v_min_u32_e32 v2, v2, v10
	v_max_u32_e32 v10, v3, v4
	v_min_u32_e32 v3, v3, v4
	v_max_u32_e32 v4, v11, v6
	v_min_u32_e32 v6, v11, v6
	v_max_u32_e32 v11, v15, v9
	v_min_u32_e32 v9, v15, v9
	v_max_u32_e32 v15, v16, v14
	v_min_u32_e32 v14, v16, v14
	v_max_u32_e32 v16, v5, v10
	v_min_u32_e32 v5, v5, v10
	v_max_u32_e32 v10, v8, v4
	v_min_u32_e32 v4, v8, v4
	v_max_u32_e32 v8, v13, v12
	v_min_u32_e32 v12, v13, v12
	v_max_u32_e32 v13, v0, v2
	v_min_u32_e32 v0, v0, v2
	v_max_u32_e32 v2, v1, v3
	v_min_u32_e32 v1, v1, v3
	v_max_u32_e32 v3, v7, v6
	v_min_u32_e32 v6, v7, v6
	v_max_u32_e32 v7, v11, v16
	v_min_u32_e32 v11, v11, v16
	v_max_u32_e32 v16, v15, v10
	v_min_u32_e32 v10, v15, v10
	v_max_u32_e32 v15, v9, v5
	v_min_u32_e32 v5, v9, v5
	v_max_u32_e32 v9, v14, v4
	v_min_u32_e32 v4, v14, v4
	v_max_u32_e32 v14, v8, v2
	v_min_u32_e32 v2, v8, v2
	v_max_u32_e32 v8, v13, v3
	v_min_u32_e32 v3, v13, v3
	v_max_u32_e32 v13, v12, v1
	v_min_u32_e32 v1, v12, v1
	v_max_u32_e32 v12, v0, v6
	v_min_u32_e32 v0, v0, v6
	v_max_u32_e32 v6, v7, v16
	v_min_u32_e32 v7, v7, v16
	v_max_u32_e32 v16, v11, v10
	v_min_u32_e32 v10, v11, v10
	v_max_u32_e32 v11, v15, v9
	v_min_u32_e32 v9, v15, v9
	v_max_u32_e32 v15, v5, v4
	v_min_u32_e32 v4, v5, v4
	v_max_u32_e32 v5, v14, v8
	v_min_u32_e32 v8, v14, v8
	v_max_u32_e32 v14, v2, v3
	v_min_u32_e32 v2, v2, v3
	v_max_u32_e32 v3, v13, v12
	v_min_u32_e32 v12, v13, v12
	v_max_u32_e32 v13, v1, v0
	v_min_u32_e32 v0, v1, v0
	ds_bpermute_b32 v1, v162, v6
	ds_bpermute_b32 v17, v162, v7
	ds_bpermute_b32 v18, v162, v16
	ds_bpermute_b32 v19, v162, v10
	ds_bpermute_b32 v20, v162, v11
	ds_bpermute_b32 v21, v162, v9
	ds_bpermute_b32 v22, v162, v15
	ds_bpermute_b32 v23, v162, v4
	ds_bpermute_b32 v24, v162, v5
	ds_bpermute_b32 v25, v162, v8
	ds_bpermute_b32 v26, v162, v14
	ds_bpermute_b32 v27, v162, v2
	ds_bpermute_b32 v28, v162, v3
	ds_bpermute_b32 v29, v162, v12
	ds_bpermute_b32 v30, v162, v13
	ds_bpermute_b32 v31, v162, v0
	s_waitcnt lgkmcnt(4)
	v_max_u32_e32 v11, v11, v27
	s_waitcnt lgkmcnt(3)
	v_max_u32_e32 v10, v10, v28
	s_waitcnt lgkmcnt(2)
	v_max_u32_e32 v16, v16, v29
	s_waitcnt lgkmcnt(1)
	v_max_u32_e32 v7, v7, v30
	s_waitcnt lgkmcnt(0)
	v_max_u32_e32 v6, v6, v31
	v_max_u32_e32 v9, v9, v26
	v_max_u32_e32 v15, v15, v25
	v_max_u32_e32 v4, v4, v24
	v_max_u32_e32 v5, v5, v23
	v_max_u32_e32 v8, v8, v22
	v_max_u32_e32 v14, v14, v21
	v_max_u32_e32 v2, v2, v20
	v_max_u32_e32 v3, v3, v19
	v_max_u32_e32 v12, v12, v18
	v_max_u32_e32 v13, v13, v17
	v_max_u32_e32 v0, v0, v1
	v_max_u32_e32 v1, v6, v5
	v_min_u32_e32 v5, v6, v5
	v_max_u32_e32 v6, v7, v8
	v_min_u32_e32 v7, v7, v8
	v_max_u32_e32 v8, v16, v14
	v_min_u32_e32 v14, v16, v14
	v_max_u32_e32 v16, v10, v2
	v_min_u32_e32 v2, v10, v2
	v_max_u32_e32 v10, v11, v3
	v_min_u32_e32 v3, v11, v3
	v_max_u32_e32 v11, v9, v12
	v_min_u32_e32 v9, v9, v12
	v_max_u32_e32 v12, v15, v13
	v_min_u32_e32 v13, v15, v13
	v_max_u32_e32 v15, v4, v0
	v_min_u32_e32 v0, v4, v0
	v_max_u32_e32 v4, v1, v10
	v_min_u32_e32 v1, v1, v10
	v_max_u32_e32 v10, v6, v11
	v_min_u32_e32 v6, v6, v11
	v_max_u32_e32 v11, v8, v12
	v_min_u32_e32 v8, v8, v12
	v_max_u32_e32 v12, v16, v15
	v_min_u32_e32 v15, v16, v15
	v_max_u32_e32 v16, v5, v3
	v_min_u32_e32 v3, v5, v3
	v_max_u32_e32 v5, v7, v9
	v_min_u32_e32 v7, v7, v9
	v_max_u32_e32 v9, v14, v13
	v_min_u32_e32 v13, v14, v13
	v_max_u32_e32 v14, v2, v0
	v_min_u32_e32 v0, v2, v0
	v_max_u32_e32 v2, v4, v11
	v_min_u32_e32 v4, v4, v11
	v_max_u32_e32 v11, v10, v12
	v_min_u32_e32 v10, v10, v12
	v_max_u32_e32 v12, v1, v8
	v_min_u32_e32 v8, v1, v8
	v_max_u32_e32 v17, v6, v15
	v_min_u32_e32 v6, v6, v15
	v_max_u32_e32 v15, v16, v9
	v_min_u32_e32 v9, v16, v9
	v_max_u32_e32 v18, v5, v14
	v_min_u32_e32 v5, v5, v14
	v_max_u32_e32 v19, v3, v13
	v_min_u32_e32 v20, v3, v13
	v_max_u32_e32 v21, v7, v0
	v_min_u32_e32 v22, v7, v0
	v_max_u32_e32 v16, v2, v11
	v_min_u32_e32 v3, v2, v11
	v_max_u32_e32 v0, v4, v10
	v_min_u32_e32 v10, v4, v10
	v_max_u32_e32 v1, v12, v17
	v_min_u32_e32 v11, v12, v17
	v_max_u32_e32 v12, v8, v6
	v_min_u32_e32 v13, v8, v6
	v_max_u32_e32 v14, v15, v18
	v_min_u32_e32 v2, v15, v18
	v_max_u32_e32 v7, v9, v5
	v_min_u32_e32 v4, v9, v5
	v_max_u32_e32 v8, v19, v21
	v_min_u32_e32 v5, v19, v21
	v_max_u32_e32 v15, v20, v22
	v_min_u32_e32 v6, v20, v22
	s_mov_b64 s[38:39], 0
	s_and_b64 vcc, exec, s[0:1]
	s_cbranch_vccnz .LBB0_49
	v_mov_b32_e32 v119, v15
	v_mov_b32_e32 v115, v6
	v_mov_b32_e32 v101, v14
	v_mov_b32_e32 v103, v2
	v_mov_b32_e32 v96, v4
	v_mov_b32_e32 v97, v7
	v_mov_b32_e32 v107, v8
	v_mov_b32_e32 v111, v5
	v_mov_b32_e32 v158, v16
	v_mov_b32_e32 v168, v3
	v_mov_b32_e32 v165, v0
	v_mov_b32_e32 v155, v10
	v_mov_b32_e32 v123, v1
	v_mov_b32_e32 v131, v11
	v_mov_b32_e32 v135, v12
	v_mov_b32_e32 v127, v13
	s_branch .LBB0_45
